# attention loops: wait Q fragments before loop and drop in-loop vmcnt ladder; MLA LDS reads 6-deep
# speedup vs baseline: 1.0175x; 1.0009x over previous
; #define ATT_LOAD(tile) do { const size_t key0 = (size_t)(tile) * 64; \
;         _Pragma("unroll") for (int i = 0; i < G::KC; ++i) kreg[i] = *(const u32x4*)(kbase + (key0 + krow_[i]) * kstride + kcc_[i] * 8); \
;         _Pragma("unroll") for (int i = 0; i < 2; ++i) { const int cid = tid + i * 512; vreg[i] = *(const u32x4*)(vtbase + (size_t)(cid >> 3) * M + key0 + (cid & 7) * 8); } } while (0)
; template <int DQK, int MODE> ...
;     ...
;     bf16x8 qf[DQK / 16];
; #pragma unroll
;     for (int dc = 0; dc < DQK / 16; ++dc) qf[dc] = *(const bf16x8*)(qptr + dc * 16 + hh * 8);
;     f32x16 O[4];
; #pragma unroll
;     for (int i = 0; i < 4; ++i)
; #pragma unroll
;         for (int j = 0; j < 16; ++j) O[i][j] = 0.f;
;     float m = m_init, l = l_init;
;     const int nt = tile_hi - tile_lo;
;     u32x4 kreg[G::KC], vreg[2];
;     int krow_[G::KC], kcc_[G::KC];
; #pragma unroll
;     for (int i = 0; i < G::KC; ++i) { const int cid = tid + i * 512; krow_[i] = cid / (DQK / 8); kcc_[i] = cid % (DQK / 8); }
;     ...
;     const bool late = __builtin_amdgcn_readfirstlane(tid >> 6) >= 4;
;     bf16x8 pf[4]; bool have_pf = false; int vprev = 0;
; #pragma unroll
;     for (int i = 0; i < 4; ++i) pf[i] = (bf16x8){0, 0, 0, 0, 0, 0, 0, 0};
;     ATT_LOAD(tile_lo); ATT_WRITE(0, 0);
;     __syncthreads();
; __global__ void __launch_bounds__(NTHREADS, 2) fwd_megakernel(Params P) {
;     ...
;             int uu = u; if (G == 256) { const int b = u & 255, x = b & 7, j = b >> 3; uu = (u < 256) ? (x * 2 + (j >> 4)) * 16 + (j & 15) : 256 + (x * 4 + (j >> 3)) * 8 + (j & 7); }
;             if (uu < 256) { const int s = uu >> 7; seqbase = s * 4096; T = 4096; h = (uu >> 4) & 7; qb = uu & 15; }
;             else { const int v = uu - 256; const int s = v >> 6; seqbase = 8192 + s * 2048; T = 2048; h = (v >> 3) & 7; qb = v & 7; }
;             const int tq = seqbase + qb * 256 + wave * 32 + (lane & 31);
;             const int t0 = seqbase >> 6, t1 = (seqbase + T) >> 6;
;             attn_unit<192, 0>(lds, QM + (size_t)tq * 1536 + h * 192, KM + h * 192, 1536, VTM + (size_t)(h * 128) * M, t0, t1, t0, t1, 0, 0, -1e30f, 0.f, OC + (size_t)tq * 2048 + h * 128);
.LBB0_403:
	s_lshr_b32 s16, s12, s60
	s_and_b32 s12, s12, s58
	s_lshl_b32 s12, s12, 8
	s_add_i32 s12, s33, s12
	s_and_b32 s86, s16, 7
	v_add_u32_e32 v188, s12, v210
	s_add_i32 s12, s33, s59
	v_mov_b64_e32 v[2:3], s[8:9]
	s_waitcnt vmcnt(5)
	v_mov_b32_e32 v18, v202
	s_ashr_i32 s87, s12, 6
	v_mad_i64_i32 v[2:3], s[60:61], v188, s80, v[2:3]
	s_mul_i32 s12, s86, 0x180
	v_lshl_add_u64 v[2:3], v[2:3], 0, s[12:13]
	v_bfe_u32 v183, v18, 5, 1
	v_lshlrev_b32_e32 v190, 4, v183
	v_mov_b32_e32 v191, v1
	v_mul_hi_i32 v0, v18, s81
	s_waitcnt vmcnt(4)
	v_lshl_add_u64 v[20:21], v[2:3], 0, v[190:191]
	v_lshrrev_b32_e32 v2, 31, v0
	v_ashrrev_i32_e32 v0, 2, v0
	v_add_u32_e32 v2, v0, v2
	v_mul_lo_u32 v0, v2, 24
	s_waitcnt vmcnt(2)
	v_add_u32_e32 v28, 0x200, v18
	v_sub_u32_e32 v19, v18, v0
	v_mul_hi_i32 v0, v28, s81
	v_lshrrev_b32_e32 v3, 31, v0
	v_ashrrev_i32_e32 v0, 2, v0
	v_add_u32_e32 v4, v0, v3
	v_mul_lo_u32 v0, v4, 24
	s_ashr_i32 s58, s33, 6
	v_sub_u32_e32 v29, v28, v0
	v_add_u32_e32 v0, 0x400, v18
	s_add_u32 s60, s72, s12
	v_mul_hi_i32 v3, v0, s81
	s_addc_u32 s61, s73, 0
	s_lshl_b32 s66, s86, 22
	v_lshrrev_b32_e32 v5, 31, v3
	v_ashrrev_i32_e32 v3, 2, v3
	s_add_u32 s16, s74, s66
	v_add_u32_e32 v6, v3, v5
	s_addc_u32 s17, s75, 0
	v_mul_lo_u32 v3, v6, 24
	s_ashr_i32 s59, s58, 31
	v_sub_u32_e32 v30, v0, v3
	s_lshl_b64 s[62:63], s[58:59], 6
	v_ashrrev_i32_e32 v3, 31, v2
	v_lshl_add_u64 v[8:9], s[62:63], 0, v[2:3]
	v_mov_b64_e32 v[12:13], s[60:61]
	v_mad_u64_u32 v[10:11], s[60:61], v8, s80, v[12:13]
	v_lshlrev_b32_e32 v8, 3, v19
	v_mad_i32_i24 v11, v9, s80, v11
	v_ashrrev_i32_e32 v9, 31, v8
	v_ashrrev_i32_e32 v5, 31, v4
	v_lshl_add_u64 v[14:15], v[8:9], 1, v[10:11]
	v_lshl_add_u64 v[10:11], s[62:63], 0, v[4:5]
	v_mad_u64_u32 v[16:17], s[60:61], v10, s80, v[12:13]
	v_lshlrev_b32_e32 v10, 3, v29
	v_mad_i32_i24 v17, v11, s80, v17
	v_ashrrev_i32_e32 v11, 31, v10
	v_ashrrev_i32_e32 v7, 31, v6
	global_load_dwordx4 v[112:115], v[20:21], off
	global_load_dwordx4 v[116:119], v[20:21], off offset:32
	v_lshl_add_u64 v[16:17], v[10:11], 1, v[16:17]
	global_load_dwordx4 v[120:123], v[14:15], off
	global_load_dwordx4 v[124:127], v[16:17], off
	v_lshl_add_u64 v[14:15], s[62:63], 0, v[6:7]
	s_sub_i32 s12, s87, s58
	v_mad_u64_u32 v[16:17], s[60:61], v14, s80, v[12:13]
	s_lshl_b64 s[64:65], s[58:59], 7
	v_lshlrev_b32_e32 v12, 3, v30
	s_add_u32 s60, s16, s64
	v_lshlrev_b32_e32 v0, 4, v18
	v_ashrrev_i32_e32 v24, 3, v18
	v_mad_i32_i24 v17, v15, s80, v17
	v_ashrrev_i32_e32 v13, 31, v12
	s_addc_u32 s61, s17, s65
	v_and_b32_e32 v0, 0x70, v0
	v_ashrrev_i32_e32 v25, 31, v24
	v_lshl_add_u64 v[16:17], v[12:13], 1, v[16:17]
	v_lshl_add_u64 v[22:23], s[60:61], 0, v[0:1]
	v_lshlrev_b64 v[14:15], 15, v[24:25]
	v_lshl_add_u64 v[26:27], v[22:23], 0, v[14:15]
	global_load_dwordx4 v[132:135], v[16:17], off
	global_load_dwordx4 v[144:147], v[26:27], off
	v_ashrrev_i32_e32 v26, 3, v28
	v_ashrrev_i32_e32 v27, 31, v26
	v_lshlrev_b64 v[16:17], 15, v[26:27]
	v_lshl_add_u64 v[22:23], v[22:23], 0, v[16:17]
	global_load_dwordx4 v[176:179], v[22:23], off
	global_load_dwordx4 v[128:131], v[20:21], off offset:64
	global_load_dwordx4 v[136:139], v[20:21], off offset:96
	global_load_dwordx4 v[140:143], v[20:21], off offset:128
	global_load_dwordx4 v[148:151], v[20:21], off offset:160
	global_load_dwordx4 v[152:155], v[20:21], off offset:192
	global_load_dwordx4 v[156:159], v[20:21], off offset:224
	global_load_dwordx4 v[160:163], v[20:21], off offset:256
	global_load_dwordx4 v[164:167], v[20:21], off offset:288
	global_load_dwordx4 v[168:171], v[20:21], off offset:320
	global_load_dwordx4 v[172:175], v[20:21], off offset:352
	v_mul_lo_u32 v189, v2, s82
	v_lshlrev_b32_e32 v213, 4, v19
	v_readfirstlane_b32 s16, v18
	v_add3_u32 v3, 0, v189, v213
	v_mul_lo_u32 v214, v4, s82
	v_lshlrev_b32_e32 v215, 4, v29
	v_mul_lo_u32 v216, v6, s82
	v_lshlrev_b32_e32 v217, 4, v30
	v_add_u32_e32 v218, 0, v0
	v_mul_lo_u32 v219, v24, s83
	s_cmpk_gt_i32 s16, 0xff
	v_add_u32_e32 v0, v218, v219
	v_mul_lo_u32 v220, v26, s83
	s_cselect_b64 s[60:61], -1, 0
	s_cmpk_lt_i32 s16, 0x100
	v_and_b32_e32 v191, 31, v18
	s_cselect_b64 s[62:63], -1, 0
	s_cmp_lt_i32 s12, 1
	s_waitcnt vmcnt(14)
	ds_write_b128 v3, v[120:123]
	v_add3_u32 v3, 0, v214, v215
	s_waitcnt vmcnt(13)
	ds_write_b128 v3, v[124:127]
	v_add3_u32 v3, 0, v216, v217
	s_waitcnt vmcnt(12)
	ds_write_b128 v3, v[132:135]
	s_waitcnt vmcnt(11)
	ds_write_b128 v0, v[144:147] offset:51200
	v_add_u32_e32 v0, v218, v220
	s_waitcnt vmcnt(10)
	ds_write_b128 v0, v[176:179] offset:51200
	s_waitcnt lgkmcnt(0)
	s_barrier
; #define ATT_LOAD(tile) do { const size_t key0 = (size_t)(tile) * 64; \
;         _Pragma("unroll") for (int i = 0; i < G::KC; ++i) kreg[i] = *(const u32x4*)(kbase + (key0 + krow_[i]) * kstride + kcc_[i] * 8); \
;         _Pragma("unroll") for (int i = 0; i < 2; ++i) { const int cid = tid + i * 512; vreg[i] = *(const u32x4*)(vtbase + (size_t)(cid >> 3) * M + key0 + (cid & 7) * 8); } } while (0)
; template <int DQK, int MODE> ...
;     ...
;     f32x16 O[4];
; #pragma unroll
;     for (int i = 0; i < 4; ++i)
; #pragma unroll
;         for (int j = 0; j < 16; ++j) O[i][j] = 0.f;
;     float m = m_init, l = l_init;
;     const int nt = tile_hi - tile_lo;
;     u32x4 kreg[G::KC], vreg[2];
;     int krow_[G::KC], kcc_[G::KC];
; #pragma unroll
;     for (int i = 0; i < G::KC; ++i) { const int cid = tid + i * 512; krow_[i] = cid / (DQK / 8); kcc_[i] = cid % (DQK / 8); }
;     ...
;     const bool late = __builtin_amdgcn_readfirstlane(tid >> 6) >= 4;
;     bf16x8 pf[4]; bool have_pf = false; int vprev = 0;
; #pragma unroll
;     for (int i = 0; i < 4; ++i) pf[i] = (bf16x8){0, 0, 0, 0, 0, 0, 0, 0};
;     ATT_LOAD(tile_lo); ATT_WRITE(0, 0);
;     __syncthreads();
;     int vcur = 0;
	s_cbranch_scc1 .LBB0_428
	s_add_u32 s16, s66, s64
	s_addc_u32 s17, 0, s65
	v_lshl_add_u32 v0, v183, 4, 0
	s_add_u32 s64, s16, 0xc400080
	v_mad_u32_u24 v221, v191, s83, v0
	v_mad_u32_u24 v222, v191, s82, v0
	s_addc_u32 s65, s17, 0
	v_and_b32_e32 v0, 7, v18
	v_lshl_add_u64 v[14:15], s[64:65], 0, v[14:15]
	v_lshlrev_b32_e32 v0, 4, v0
	s_mul_i32 s17, s58, 0x30000
	v_lshl_add_u64 v[192:193], v[14:15], 0, v[0:1]
	v_lshl_add_u64 v[14:15], s[64:65], 0, v[16:17]
	s_mul_hi_i32 s16, s58, 0x30000
	s_add_u32 s64, s17, 0x9430000
	s_addc_u32 s65, s16, 0
	v_lshl_add_u64 v[194:195], v[14:15], 0, v[0:1]
	v_mov_b64_e32 v[14:15], s[64:65]
	v_mad_i64_i32 v[6:7], s[64:65], v6, s80, v[14:15]
	v_mad_i64_i32 v[4:5], s[64:65], v4, s80, v[14:15]
	v_mad_i64_i32 v[2:3], s[64:65], v2, s80, v[14:15]
	v_mad_u64_u32 v[6:7], s[64:65], s86, v211, v[6:7]
	v_mad_u64_u32 v[4:5], s[64:65], s86, v211, v[4:5]
	v_mad_u64_u32 v[2:3], s[64:65], s86, v211, v[2:3]
	v_mov_b32_e32 v14, v1
	v_mov_b32_e32 v15, v1
	v_lshl_add_u64 v[196:197], v[12:13], 1, v[6:7]
	v_lshl_add_u64 v[198:199], v[10:11], 1, v[4:5]
	v_lshl_add_u64 v[200:201], v[8:9], 1, v[2:3]
	v_mov_b32_e32 v0, v1
	v_mov_b32_e32 v2, v1
	v_mov_b32_e32 v3, v1
	v_mov_b32_e32 v4, v1
	v_mov_b32_e32 v5, v1
	v_mov_b32_e32 v6, v1
	v_mov_b32_e32 v7, v1
	v_mov_b32_e32 v8, v1
	v_mov_b32_e32 v9, v1
	v_mov_b32_e32 v10, v1
	v_mov_b32_e32 v11, v1
	v_mov_b32_e32 v12, v1
	v_mov_b32_e32 v13, v1
	v_mov_b64_e32 v[78:79], v[14:15]
	v_mov_b64_e32 v[62:63], v[14:15]
	v_mov_b64_e32 v[46:47], v[14:15]
	v_mov_b64_e32 v[30:31], v[14:15]
	s_mov_b32 s59, 0
	s_mov_b64 s[64:65], 0
	v_mov_b32_e32 v212, 0
	v_mov_b32_e32 v223, 0xf149f2ca
	v_mov_b32_e32 v92, 0
	v_mov_b32_e32 v93, 0
	v_mov_b32_e32 v94, 0
	v_mov_b32_e32 v95, 0
	v_mov_b32_e32 v88, 0
	v_mov_b32_e32 v89, 0
	v_mov_b32_e32 v90, 0
	v_mov_b32_e32 v91, 0
	v_mov_b32_e32 v84, 0
	v_mov_b32_e32 v85, 0
	v_mov_b32_e32 v86, 0
	v_mov_b32_e32 v87, 0
	v_mov_b32_e32 v80, 0
	v_mov_b32_e32 v81, 0
	v_mov_b32_e32 v82, 0
	v_mov_b32_e32 v83, 0
	v_mov_b64_e32 v[76:77], v[12:13]
	v_mov_b64_e32 v[74:75], v[10:11]
	v_mov_b64_e32 v[72:73], v[8:9]
	v_mov_b64_e32 v[70:71], v[6:7]
	v_mov_b64_e32 v[68:69], v[4:5]
	v_mov_b64_e32 v[66:67], v[2:3]
	v_mov_b64_e32 v[64:65], v[0:1]
	v_mov_b64_e32 v[60:61], v[12:13]
	v_mov_b64_e32 v[58:59], v[10:11]
	v_mov_b64_e32 v[56:57], v[8:9]
	v_mov_b64_e32 v[54:55], v[6:7]
	v_mov_b64_e32 v[52:53], v[4:5]
	v_mov_b64_e32 v[50:51], v[2:3]
	v_mov_b64_e32 v[48:49], v[0:1]
	v_mov_b64_e32 v[44:45], v[12:13]
	v_mov_b64_e32 v[42:43], v[10:11]
	v_mov_b64_e32 v[40:41], v[8:9]
	v_mov_b64_e32 v[38:39], v[6:7]
	v_mov_b64_e32 v[36:37], v[4:5]
	v_mov_b64_e32 v[34:35], v[2:3]
	v_mov_b64_e32 v[32:33], v[0:1]
	v_mov_b64_e32 v[28:29], v[12:13]
	v_mov_b64_e32 v[26:27], v[10:11]
	v_mov_b64_e32 v[24:25], v[8:9]
	v_mov_b64_e32 v[22:23], v[6:7]
	v_mov_b64_e32 v[20:21], v[4:5]
	v_mov_b64_e32 v[18:19], v[2:3]
	v_mov_b64_e32 v[16:17], v[0:1]
	s_mov_b32 s88, 0
	s_mov_b32 s90, 0
	s_waitcnt vmcnt(0)

; #define LAS __attribute__((address_space(3)))
; #define ATT_LOAD(tile) do { const size_t key0 = (size_t)(tile) * 64; \
;         _Pragma("unroll") for (int i = 0; i < G::KC; ++i) kreg[i] = *(const u32x4*)(kbase + (key0 + krow_[i]) * kstride + kcc_[i] * 8); \
;         _Pragma("unroll") for (int i = 0; i < 2; ++i) { const int cid = tid + i * 512; vreg[i] = *(const u32x4*)(vtbase + (size_t)(cid >> 3) * M + key0 + (cid & 7) * 8); } } while (0)
; template <int DQK, int MODE> ...
;     ...
;     const bool late = __builtin_amdgcn_readfirstlane(tid >> 6) >= 4;
;     bf16x8 pf[4]; bool have_pf = false; int vprev = 0;
; #pragma unroll
;     for (int i = 0; i < 4; ++i) pf[i] = (bf16x8){0, 0, 0, 0, 0, 0, 0, 0};
;     ATT_LOAD(tile_lo); ATT_WRITE(0, 0);
;     __syncthreads();
;     int vcur = 0;
;     for (int it = 0; it < nt; ++it) {
;         const int tile = tile_lo + it, buf = it & 1;
;         const int vnext = (vcur == 2) ? 0 : vcur + 1;
;         if (it + 1 < nt) ATT_LOAD(tile + 1);
;         if (late && have_pf) { ATT_PV(vprev); have_pf = false; }
;         if (tile >= wlo && tile < whi) {
;             const LAS unsigned char* kb = lds + buf * G::KBUF;
;             f32x16 S0, S1;
; #pragma unroll
;             for (int j = 0; j < 16; ++j) { S0[j] = 0.f; S1[j] = 0.f; }
; #pragma unroll
;             for (int dc = 0; dc < DQK / 16; ++dc) {
;                 const bf16x8 ka = *(const LAS bf16x8*)(kb + r32 * G::KROW + dc * 32 + hh * 16);
;                 const bf16x8 kb2 = *(const LAS bf16x8*)(kb + (32 + r32) * G::KROW + dc * 32 + hh * 16);
;                 S0 = __builtin_amdgcn_mfma_f32_32x32x16_bf16(ka, qf[dc], S0, 0, 0, 0);
;                 S1 = __builtin_amdgcn_mfma_f32_32x32x16_bf16(kb2, qf[dc], S1, 0, 0, 0);
;             }
;     ...
;             float pmax = S0[0];
; #pragma unroll
;             for (int j = 1; j < 16; ++j) pmax = fmaxf(pmax, S0[j]);
; #pragma unroll
;             for (int j = 0; j < 16; ++j) pmax = fmaxf(pmax, S1[j]);
;             { auto rr = __builtin_amdgcn_permlane32_swap(__float_as_uint(pmax), __float_as_uint(pmax), false, false); pmax = fmaxf(__uint_as_float(rr[0]), __uint_as_float(rr[1])); }
;             if (!__all(pmax - m <= 8.0f)) {
.LBB0_409:
	s_mul_i32 s16, s59, 0x4800
	v_add_u32_e32 v0, s16, v221
	ds_read_b128 v[2:5], v0 offset:51200
	ds_read_b128 v[6:9], v0 offset:51232
	ds_read_b128 v[236:239], v0 offset:51264
	ds_read_b128 v[240:243], v0 offset:51296
	ds_read_b128 v[244:247], v0 offset:55808
	ds_read_b128 v[248:251], v0 offset:55840
	s_mov_b64 s[64:65], 0
	s_waitcnt lgkmcnt(5)
	v_mfma_f32_32x32x16_bf16 v[64:79], v[2:5], v[80:83], v[64:79]
	ds_read_b128 v[2:5], v0 offset:55872
	s_waitcnt lgkmcnt(5)
	v_mfma_f32_32x32x16_bf16 v[64:79], v[6:9], v[84:87], v[64:79]
	ds_read_b128 v[6:9], v0 offset:55904
	s_waitcnt lgkmcnt(5)
	v_mfma_f32_32x32x16_bf16 v[64:79], v[236:239], v[88:91], v[64:79]
	ds_read_b128 v[236:239], v0 offset:60416
	s_waitcnt lgkmcnt(5)
	v_mfma_f32_32x32x16_bf16 v[64:79], v[240:243], v[92:95], v[64:79]
	ds_read_b128 v[240:243], v0 offset:60448
	s_waitcnt lgkmcnt(5)
	v_mfma_f32_32x32x16_bf16 v[48:63], v[244:247], v[80:83], v[48:63]
	ds_read_b128 v[244:247], v0 offset:60480
	s_waitcnt lgkmcnt(5)
	v_mfma_f32_32x32x16_bf16 v[48:63], v[248:251], v[84:87], v[48:63]
	ds_read_b128 v[248:251], v0 offset:60512
	s_waitcnt lgkmcnt(5)
	v_mfma_f32_32x32x16_bf16 v[48:63], v[2:5], v[88:91], v[48:63]
	ds_read_b128 v[2:5], v0 offset:65024
	s_waitcnt lgkmcnt(5)
	v_mfma_f32_32x32x16_bf16 v[48:63], v[6:9], v[92:95], v[48:63]
	ds_read_b128 v[6:9], v0 offset:65056
	s_waitcnt lgkmcnt(5)
	v_mfma_f32_32x32x16_bf16 v[32:47], v[236:239], v[80:83], v[32:47]
	ds_read_b128 v[236:239], v0 offset:65088
	s_waitcnt lgkmcnt(5)
	v_mfma_f32_32x32x16_bf16 v[32:47], v[240:243], v[84:87], v[32:47]
	ds_read_b128 v[240:243], v0 offset:65120
	s_waitcnt lgkmcnt(5)
	v_mfma_f32_32x32x16_bf16 v[32:47], v[244:247], v[88:91], v[32:47]
	s_waitcnt lgkmcnt(4)
	v_mfma_f32_32x32x16_bf16 v[32:47], v[248:251], v[92:95], v[32:47]
	s_waitcnt lgkmcnt(3)
	v_mfma_f32_32x32x16_bf16 v[16:31], v[2:5], v[80:83], v[16:31]
	s_waitcnt lgkmcnt(2)
	v_mfma_f32_32x32x16_bf16 v[16:31], v[6:9], v[84:87], v[16:31]
	s_waitcnt lgkmcnt(1)
	v_mfma_f32_32x32x16_bf16 v[16:31], v[236:239], v[88:91], v[16:31]
	s_waitcnt lgkmcnt(0)
	v_mfma_f32_32x32x16_bf16 v[16:31], v[240:243], v[92:95], v[16:31]
	s_add_i32 s16, s58, s90
	s_and_b32 s90, s90, 1
	s_cmp_ge_i32 s16, s87
	s_cbranch_scc1 .LBB0_416
.LBB0_410:
	s_mul_i32 s16, s90, 0x6400
	v_add_u32_e32 v0, s16, v222
	ds_read_b128 v[2:5], v0
	ds_read_b128 v[6:9], v0 offset:32
	ds_read_b128 v[236:239], v0 offset:64
	ds_read_b128 v[240:243], v0 offset:96
	ds_read_b128 v[244:247], v0 offset:128
	ds_read_b128 v[248:251], v0 offset:160
	s_waitcnt lgkmcnt(5)
	v_mfma_f32_32x32x16_bf16 v[80:95], v[2:5], v[112:115], 0
	ds_read_b128 v[2:5], v0 offset:192
	s_waitcnt lgkmcnt(5)
	v_mfma_f32_32x32x16_bf16 v[80:95], v[6:9], v[116:119], v[80:95]
	ds_read_b128 v[6:9], v0 offset:224
	s_waitcnt lgkmcnt(5)
	v_mfma_f32_32x32x16_bf16 v[80:95], v[236:239], v[128:131], v[80:95]
	ds_read_b128 v[236:239], v0 offset:256
	s_waitcnt lgkmcnt(5)
	v_mfma_f32_32x32x16_bf16 v[80:95], v[240:243], v[136:139], v[80:95]
	ds_read_b128 v[240:243], v0 offset:288
	s_waitcnt lgkmcnt(5)
	v_mfma_f32_32x32x16_bf16 v[80:95], v[244:247], v[140:143], v[80:95]
	ds_read_b128 v[244:247], v0 offset:320
	s_waitcnt lgkmcnt(5)
	v_mfma_f32_32x32x16_bf16 v[80:95], v[248:251], v[148:151], v[80:95]
	ds_read_b128 v[248:251], v0 offset:352
	s_waitcnt lgkmcnt(5)
	v_mfma_f32_32x32x16_bf16 v[80:95], v[2:5], v[152:155], v[80:95]
	ds_read_b128 v[2:5], v0 offset:12800
	s_waitcnt lgkmcnt(5)
	v_mfma_f32_32x32x16_bf16 v[80:95], v[6:9], v[156:159], v[80:95]
	ds_read_b128 v[6:9], v0 offset:12832
	s_waitcnt lgkmcnt(5)
	v_mfma_f32_32x32x16_bf16 v[80:95], v[236:239], v[160:163], v[80:95]
	ds_read_b128 v[236:239], v0 offset:12864
	s_waitcnt lgkmcnt(5)
	v_mfma_f32_32x32x16_bf16 v[80:95], v[240:243], v[164:167], v[80:95]
	ds_read_b128 v[240:243], v0 offset:12896
	s_waitcnt lgkmcnt(5)
	v_mfma_f32_32x32x16_bf16 v[80:95], v[244:247], v[168:171], v[80:95]
	ds_read_b128 v[244:247], v0 offset:12928
	s_waitcnt lgkmcnt(5)
	v_mfma_f32_32x32x16_bf16 v[80:95], v[248:251], v[172:175], v[80:95]
	ds_read_b128 v[248:251], v0 offset:12960
	s_waitcnt lgkmcnt(5)
	v_mfma_f32_32x32x16_bf16 v[96:111], v[2:5], v[112:115], 0
	ds_read_b128 v[2:5], v0 offset:12992
	s_nop 7
	v_max_f32_e32 v10, v80, v80
	s_waitcnt lgkmcnt(5)
	v_mfma_f32_32x32x16_bf16 v[96:111], v[6:9], v[116:119], v[96:111]
	ds_read_b128 v[6:9], v0 offset:13024
	s_waitcnt lgkmcnt(5)
	v_mfma_f32_32x32x16_bf16 v[96:111], v[236:239], v[128:131], v[96:111]
	ds_read_b128 v[236:239], v0 offset:13056
	s_waitcnt lgkmcnt(5)
	v_mfma_f32_32x32x16_bf16 v[96:111], v[240:243], v[136:139], v[96:111]
	ds_read_b128 v[240:243], v0 offset:13088
	s_waitcnt lgkmcnt(5)
	v_mfma_f32_32x32x16_bf16 v[96:111], v[244:247], v[140:143], v[96:111]
	ds_read_b128 v[244:247], v0 offset:13120
	s_waitcnt lgkmcnt(5)
	v_mfma_f32_32x32x16_bf16 v[96:111], v[248:251], v[148:151], v[96:111]
	ds_read_b128 v[248:251], v0 offset:13152
	s_waitcnt lgkmcnt(5)
	v_mfma_f32_32x32x16_bf16 v[96:111], v[2:5], v[152:155], v[96:111]
	s_waitcnt lgkmcnt(4)
	v_mfma_f32_32x32x16_bf16 v[96:111], v[6:9], v[156:159], v[96:111]
	s_waitcnt lgkmcnt(3)
	v_mfma_f32_32x32x16_bf16 v[96:111], v[236:239], v[160:163], v[96:111]
	s_waitcnt lgkmcnt(2)
	v_mfma_f32_32x32x16_bf16 v[96:111], v[240:243], v[164:167], v[96:111]
	v_max_f32_e32 v0, v81, v81
	v_max_f32_e32 v0, v10, v0
	v_max3_f32 v0, v0, v82, v83
	v_max3_f32 v0, v0, v84, v85
	v_max3_f32 v0, v0, v86, v87
	v_max3_f32 v0, v0, v88, v89
	s_waitcnt lgkmcnt(1)
	v_mfma_f32_32x32x16_bf16 v[96:111], v[244:247], v[168:171], v[96:111]
	v_max3_f32 v0, v0, v90, v91
	v_max3_f32 v0, v0, v92, v93
	v_max3_f32 v0, v0, v94, v95
	s_waitcnt lgkmcnt(0)
	v_mfma_f32_32x32x16_bf16 v[96:111], v[248:251], v[172:175], v[96:111]
	s_nop 11
	v_max3_f32 v0, v0, v96, v97
	v_max3_f32 v0, v0, v98, v99
	v_max3_f32 v0, v0, v100, v101
	v_max3_f32 v0, v0, v102, v103
	v_max3_f32 v0, v0, v104, v105
	v_max3_f32 v0, v0, v106, v107
	v_max3_f32 v0, v0, v108, v109
	v_max3_f32 v0, v0, v110, v111
	v_mov_b32_e32 v2, v0
	s_nop 1
	v_permlane32_swap_b32_e32 v0, v2
	v_max_f32_e32 v2, v2, v2
	v_max_f32_e32 v0, v0, v0
	v_max_f32_e32 v0, v0, v2
	v_sub_f32_e32 v2, v0, v223
	v_cmp_ge_f32_e32 vcc, s84, v2
	s_cmp_eq_u64 vcc, exec
	s_cbranch_scc1 .LBB0_412
; __device__ __forceinline__ unsigned cvt_pk_bf16(float lo, float hi) { unsigned r; asm volatile("v_cvt_pk_bf16_f32 %0, %1, %2" : "=v"(r) : "v"(lo), "v"(hi)); return r; }
; template <int DQK, int MODE> ...
;     ...
;             if (!__all(pmax - m <= 8.0f)) {
;                 const float mn2 = fmaxf(m, pmax); const float alpha = __builtin_amdgcn_exp2f(m - mn2); m = mn2; l *= alpha;
; #pragma unroll
;                 for (int i = 0; i < 4; ++i)
; #pragma unroll
;                     for (int j = 0; j < 16; ++j) O[i][j] *= alpha;
;             }
;             const float mn = m;
;             float ps = 0.f;
; #pragma unroll
;             for (int j = 0; j < 16; ++j) { S0[j] = __builtin_amdgcn_exp2f(S0[j] - mn); S1[j] = __builtin_amdgcn_exp2f(S1[j] - mn); ps += S0[j] + S1[j]; }
;             l += ps;
;             { u32x4 w;
;               w.x = cvt_pk_bf16(S0[0], S0[1]); w.y = cvt_pk_bf16(S0[2], S0[3]); w.z = cvt_pk_bf16(S0[4], S0[5]); w.w = cvt_pk_bf16(S0[6], S0[7]); pf[0] = *(bf16x8*)&w;
;               w.x = cvt_pk_bf16(S0[8], S0[9]); w.y = cvt_pk_bf16(S0[10], S0[11]); w.z = cvt_pk_bf16(S0[12], S0[13]); w.w = cvt_pk_bf16(S0[14], S0[15]); pf[1] = *(bf16x8*)&w;
;               w.x = cvt_pk_bf16(S1[0], S1[1]); w.y = cvt_pk_bf16(S1[2], S1[3]); w.z = cvt_pk_bf16(S1[4], S1[5]); w.w = cvt_pk_bf16(S1[6], S1[7]); pf[2] = *(bf16x8*)&w;
;               w.x = cvt_pk_bf16(S1[8], S1[9]); w.y = cvt_pk_bf16(S1[10], S1[11]); w.z = cvt_pk_bf16(S1[12], S1[13]); w.w = cvt_pk_bf16(S1[14], S1[15]); pf[3] = *(bf16x8*)&w; }
;             if (!late) ATT_PV(vcur); else { have_pf = true; vprev = vcur; }
	v_max_f32_e32 v0, v0, v0
	v_max_f32_e32 v2, v223, v223
	v_max_f32_e32 v2, v2, v0
	v_sub_f32_e32 v0, v223, v2
	v_exp_f32_e32 v0, v0
	v_mov_b32_e32 v223, v2
	v_pk_mul_f32 v[78:79], v[78:79], v[0:1] op_sel_hi:[1,0]
	v_pk_mul_f32 v[76:77], v[76:77], v[0:1] op_sel_hi:[1,0]
	v_pk_mul_f32 v[74:75], v[74:75], v[0:1] op_sel_hi:[1,0]
	v_pk_mul_f32 v[72:73], v[72:73], v[0:1] op_sel_hi:[1,0]
	v_pk_mul_f32 v[70:71], v[70:71], v[0:1] op_sel_hi:[1,0]
	v_pk_mul_f32 v[68:69], v[68:69], v[0:1] op_sel_hi:[1,0]
	v_pk_mul_f32 v[66:67], v[66:67], v[0:1] op_sel_hi:[1,0]
	v_pk_mul_f32 v[64:65], v[64:65], v[0:1] op_sel_hi:[1,0]
	v_pk_mul_f32 v[62:63], v[62:63], v[0:1] op_sel_hi:[1,0]
	v_pk_mul_f32 v[60:61], v[60:61], v[0:1] op_sel_hi:[1,0]
	v_pk_mul_f32 v[58:59], v[58:59], v[0:1] op_sel_hi:[1,0]
	v_pk_mul_f32 v[56:57], v[56:57], v[0:1] op_sel_hi:[1,0]
	v_pk_mul_f32 v[54:55], v[54:55], v[0:1] op_sel_hi:[1,0]
	v_pk_mul_f32 v[52:53], v[52:53], v[0:1] op_sel_hi:[1,0]
	v_pk_mul_f32 v[50:51], v[50:51], v[0:1] op_sel_hi:[1,0]
	v_pk_mul_f32 v[48:49], v[48:49], v[0:1] op_sel_hi:[1,0]
	v_pk_mul_f32 v[46:47], v[46:47], v[0:1] op_sel_hi:[1,0]
	v_pk_mul_f32 v[44:45], v[44:45], v[0:1] op_sel_hi:[1,0]
	v_pk_mul_f32 v[42:43], v[42:43], v[0:1] op_sel_hi:[1,0]
	v_pk_mul_f32 v[40:41], v[40:41], v[0:1] op_sel_hi:[1,0]
	v_pk_mul_f32 v[38:39], v[38:39], v[0:1] op_sel_hi:[1,0]
	v_pk_mul_f32 v[36:37], v[36:37], v[0:1] op_sel_hi:[1,0]
	v_pk_mul_f32 v[34:35], v[34:35], v[0:1] op_sel_hi:[1,0]
	v_pk_mul_f32 v[32:33], v[32:33], v[0:1] op_sel_hi:[1,0]
	v_pk_mul_f32 v[30:31], v[30:31], v[0:1] op_sel_hi:[1,0]
	v_pk_mul_f32 v[28:29], v[28:29], v[0:1] op_sel_hi:[1,0]
	v_pk_mul_f32 v[26:27], v[26:27], v[0:1] op_sel_hi:[1,0]
	v_pk_mul_f32 v[24:25], v[24:25], v[0:1] op_sel_hi:[1,0]
	v_pk_mul_f32 v[22:23], v[22:23], v[0:1] op_sel_hi:[1,0]
	v_pk_mul_f32 v[20:21], v[20:21], v[0:1] op_sel_hi:[1,0]
	v_pk_mul_f32 v[18:19], v[18:19], v[0:1] op_sel_hi:[1,0]
	v_pk_mul_f32 v[16:17], v[16:17], v[0:1] op_sel_hi:[1,0]
	v_mul_f32_e32 v212, v212, v0
.LBB0_412:
	v_sub_f32_e32 v8, v101, v223
	v_sub_f32_e32 v0, v80, v223
	v_exp_f32_e32 v14, v8
	v_sub_f32_e32 v8, v86, v223
	v_sub_f32_e32 v80, v105, v223
	v_exp_f32_e32 v13, v8
	v_sub_f32_e32 v8, v102, v223
	v_exp_f32_e32 v102, v80
	v_sub_f32_e32 v80, v90, v223
	v_exp_f32_e32 v101, v80
	v_sub_f32_e32 v80, v106, v223
	v_exp_f32_e32 v225, v80
	v_sub_f32_e32 v80, v91, v223
	v_exp_f32_e32 v3, v0
	v_sub_f32_e32 v0, v96, v223
	v_exp_f32_e32 v96, v80
	v_sub_f32_e32 v80, v107, v223
	v_exp_f32_e32 v106, v80
	v_sub_f32_e32 v80, v92, v223
	v_sub_f32_e32 v6, v99, v223
	v_exp_f32_e32 v105, v80
	v_sub_f32_e32 v80, v108, v223
	v_exp_f32_e32 v10, v6
	v_sub_f32_e32 v6, v84, v223
	v_exp_f32_e32 v226, v80
	v_sub_f32_e32 v80, v93, v223
	v_exp_f32_e32 v7, v6
	v_sub_f32_e32 v6, v100, v223
	v_exp_f32_e32 v100, v80
	v_sub_f32_e32 v80, v109, v223
	v_sub_f32_e32 v4, v82, v223
	v_sub_f32_e32 v12, v103, v223
	v_exp_f32_e32 v108, v80
	v_sub_f32_e32 v80, v94, v223
	v_exp_f32_e32 v9, v0
	v_sub_f32_e32 v0, v81, v223
	v_exp_f32_e32 v5, v4
	v_sub_f32_e32 v4, v98, v223
	v_exp_f32_e32 v98, v12
	v_sub_f32_e32 v12, v88, v223
	v_exp_f32_e32 v224, v80
	v_sub_f32_e32 v80, v110, v223
	v_exp_f32_e32 v2, v0
	v_sub_f32_e32 v0, v97, v223
	v_exp_f32_e32 v97, v12
	v_sub_f32_e32 v12, v104, v223
	v_exp_f32_e32 v227, v80
	v_sub_f32_e32 v80, v95, v223
	v_exp_f32_e32 v11, v4
	v_sub_f32_e32 v4, v83, v223
	v_exp_f32_e32 v15, v6
	v_sub_f32_e32 v6, v85, v223
	v_exp_f32_e32 v99, v8
	v_sub_f32_e32 v8, v87, v223
	v_exp_f32_e32 v103, v12
	v_sub_f32_e32 v12, v89, v223
	v_exp_f32_e32 v104, v80
	v_sub_f32_e32 v80, v111, v223
	v_exp_f32_e32 v0, v0
	v_exp_f32_e32 v4, v4
	v_exp_f32_e32 v6, v6
	v_exp_f32_e32 v8, v8
	v_exp_f32_e32 v12, v12
	v_exp_f32_e32 v110, v80
	s_andn2_b64 vcc, exec, s[62:63]
	v_cvt_pk_bf16_f32 v80, v3, v2
	v_cvt_pk_bf16_f32 v81, v5, v4
	v_cvt_pk_bf16_f32 v82, v7, v6
	v_cvt_pk_bf16_f32 v83, v13, v8
	v_cvt_pk_bf16_f32 v84, v97, v12
	v_cvt_pk_bf16_f32 v85, v101, v96
	v_cvt_pk_bf16_f32 v86, v105, v100
	v_cvt_pk_bf16_f32 v87, v224, v104
	v_cvt_pk_bf16_f32 v88, v9, v0
	v_cvt_pk_bf16_f32 v89, v11, v10
	v_cvt_pk_bf16_f32 v90, v15, v14
	v_cvt_pk_bf16_f32 v91, v99, v98
	v_cvt_pk_bf16_f32 v92, v103, v102
	v_cvt_pk_bf16_f32 v93, v225, v106
	v_cvt_pk_bf16_f32 v94, v226, v108
	v_cvt_pk_bf16_f32 v95, v227, v110
	s_cbranch_vccnz .LBB0_414
	s_mul_i32 s16, s88, 0x4800
	v_add_u32_e32 v107, s16, v221
	ds_read_b128 v[228:231], v107 offset:51200
	ds_read_b128 v[232:235], v107 offset:51232
	ds_read_b128 v[236:239], v107 offset:51264
	ds_read_b128 v[240:243], v107 offset:51296
	ds_read_b128 v[244:247], v107 offset:55808
	ds_read_b128 v[248:251], v107 offset:55840
	s_waitcnt lgkmcnt(5)
	v_mfma_f32_32x32x16_bf16 v[64:79], v[228:231], v[80:83], v[64:79]
	ds_read_b128 v[228:231], v107 offset:55872
	s_waitcnt lgkmcnt(5)
	v_mfma_f32_32x32x16_bf16 v[64:79], v[232:235], v[84:87], v[64:79]
	ds_read_b128 v[232:235], v107 offset:55904
	s_waitcnt lgkmcnt(5)
	v_mfma_f32_32x32x16_bf16 v[64:79], v[236:239], v[88:91], v[64:79]
	ds_read_b128 v[236:239], v107 offset:60416
	s_waitcnt lgkmcnt(5)
	v_mfma_f32_32x32x16_bf16 v[64:79], v[240:243], v[92:95], v[64:79]
	ds_read_b128 v[240:243], v107 offset:60448
	s_waitcnt lgkmcnt(5)
	v_mfma_f32_32x32x16_bf16 v[48:63], v[244:247], v[80:83], v[48:63]
	ds_read_b128 v[244:247], v107 offset:60480
	s_waitcnt lgkmcnt(5)
	v_mfma_f32_32x32x16_bf16 v[48:63], v[248:251], v[84:87], v[48:63]
	ds_read_b128 v[248:251], v107 offset:60512
	s_waitcnt lgkmcnt(5)
	v_mfma_f32_32x32x16_bf16 v[48:63], v[228:231], v[88:91], v[48:63]
	ds_read_b128 v[228:231], v107 offset:65024
	s_waitcnt lgkmcnt(5)
	v_mfma_f32_32x32x16_bf16 v[48:63], v[232:235], v[92:95], v[48:63]
	ds_read_b128 v[232:235], v107 offset:65056
	s_waitcnt lgkmcnt(5)
	v_mfma_f32_32x32x16_bf16 v[32:47], v[236:239], v[80:83], v[32:47]
	ds_read_b128 v[236:239], v107 offset:65088
	s_waitcnt lgkmcnt(5)
	v_mfma_f32_32x32x16_bf16 v[32:47], v[240:243], v[84:87], v[32:47]
	ds_read_b128 v[240:243], v107 offset:65120
	s_waitcnt lgkmcnt(5)
	v_mfma_f32_32x32x16_bf16 v[32:47], v[244:247], v[88:91], v[32:47]
	s_waitcnt lgkmcnt(4)
	v_mfma_f32_32x32x16_bf16 v[32:47], v[248:251], v[92:95], v[32:47]
	s_waitcnt lgkmcnt(3)
	v_mfma_f32_32x32x16_bf16 v[16:31], v[228:231], v[80:83], v[16:31]
	s_waitcnt lgkmcnt(2)
	v_mfma_f32_32x32x16_bf16 v[16:31], v[232:235], v[84:87], v[16:31]
	s_waitcnt lgkmcnt(1)
	v_mfma_f32_32x32x16_bf16 v[16:31], v[236:239], v[88:91], v[16:31]
	s_waitcnt lgkmcnt(0)
	v_mfma_f32_32x32x16_bf16 v[16:31], v[240:243], v[92:95], v[16:31]
	s_branch .LBB0_415

; #define LAS __attribute__((address_space(3)))
; template <int DQK, int MODE> ...
;     ...
;     bf16x8 qf[DQK / 16];
; #pragma unroll
;     for (int dc = 0; dc < DQK / 16; ++dc) qf[dc] = *(const bf16x8*)(qptr + dc * 16 + hh * 8);
;     f32x16 O[4];
; #pragma unroll
;     for (int i = 0; i < 4; ++i)
; #pragma unroll
;         for (int j = 0; j < 16; ++j) O[i][j] = 0.f;
;     float m = m_init, l = l_init;
;     const int nt = tile_hi - tile_lo;
;     u32x4 kreg[G::KC], vreg[2];
;     int krow_[G::KC], kcc_[G::KC];
; #pragma unroll
;     for (int i = 0; i < G::KC; ++i) { const int cid = tid + i * 512; krow_[i] = cid / (DQK / 8); kcc_[i] = cid % (DQK / 8); }
;     ...
;     const bool late = __builtin_amdgcn_readfirstlane(tid >> 6) >= 4;
;     bf16x8 pf[4]; bool have_pf = false; int vprev = 0;
; #pragma unroll
;     for (int i = 0; i < 4; ++i) pf[i] = (bf16x8){0, 0, 0, 0, 0, 0, 0, 0};
;     ATT_LOAD(tile_lo); ATT_WRITE(0, 0);
;     __syncthreads();
; __global__ void __launch_bounds__(NTHREADS, 2) fwd_megakernel(Params P) {
;     ...
;             int uu = u; if (G == 256) { const int b = u & 255, x = b & 7, j = b >> 3; uu = (u < 256) ? (x * 2 + (j >> 4)) * 16 + (j & 15) : 256 + (x * 4 + (j >> 3)) * 8 + (j & 7); }
;             if (uu < 256) { const int s = uu >> 7; seqbase = s * 4096; rows = 64; h = (uu >> 4) & 7; rg = uu & 15; }
;             else { const int v = uu - 256; const int s = v >> 6; seqbase = 8192 + s * 2048; rows = 32; h = (v >> 3) & 7; rg = v & 7; }
;             { LAS float* rpbL = (LAS float*)(lds + AG<128>::RPB_OFF); for (int i = tid; i < 465; i += NTHREADS) rpbL[i] = kp->in[I_RPB][h * 465 + i] * LOG2E; }
;             const int r = rg * 4 + (wave >> 1), c = (wave & 1) * 32 + (lane & 31);
;             const int tq = seqbase + r * 64 + c;
;             const int st0 = seqbase >> 6;
;             int rs_lo = rg * 4 - 4; rs_lo = rs_lo < 0 ? 0 : (rs_lo > rows - 8 ? rows - 8 : rs_lo);
;             int rs_hi = rg * 4 + 3 - 4; rs_hi = rs_hi < 0 ? 0 : (rs_hi > rows - 8 ? rows - 8 : rs_hi);
;             int rs = r - 4; rs = rs < 0 ? 0 : (rs > rows - 8 ? rows - 8 : rs);
;             attn_unit<128, 1>(lds, NQ + (size_t)tq * 1024 + h * 128, NK + h * 128, 1024, NVT + (size_t)(h * 128) * M, st0 + rs_lo, st0 + rs_hi + 8, st0 + rs, st0 + rs + 8, c, 7 - r - st0, -1e30f, 0.f,
.LBB0_481:
	s_or_b64 exec, exec, s[62:63]
	s_and_b32 s16, s56, s74
	s_lshl_b32 s74, s16, 2
	s_add_i32 s75, s74, s61
	v_lshl_or_b32 v0, s75, 6, v178
	s_add_i32 s17, s74, -4
	s_add_i32 s33, s74, -1
	v_add_u32_e32 v160, s73, v0
	s_ashr_i32 s73, s73, 6
	s_min_i32 s17, s17, s72
	s_min_i32 s33, s33, s72
	s_lshl_b32 s56, s91, 8
	s_add_u32 s68, s80, s56
	s_addc_u32 s69, s81, 0
	s_lshl_b32 s62, s91, 22
	s_add_u32 s70, s82, s62
	s_addc_u32 s71, s83, 0
	s_add_i32 s33, s33, 8
	s_waitcnt vmcnt(6)
	v_mov_b32_e32 v14, v202
	s_cmp_eq_u32 s16, 0
	s_cselect_b32 s95, 0, s17
	v_ashrrev_i32_e32 v0, 31, v14
	v_lshrrev_b32_e32 v0, 28, v0
	v_ashrrev_i32_e32 v161, 31, v160
	s_cselect_b32 s16, 8, s33
	s_add_i32 s62, s73, s95
	v_add_u32_e32 v0, v14, v0
	v_lshlrev_b64 v[2:3], 11, v[160:161]
	v_ashrrev_i32_e32 v164, 4, v0
	v_and_b32_e32 v0, -16, v0
	s_waitcnt vmcnt(5)
	v_add_u32_e32 v16, 0x200, v14
	s_ashr_i32 s63, s62, 31
	v_lshl_add_u64 v[2:3], s[54:55], 0, v[2:3]
	v_sub_u32_e32 v15, v14, v0
	v_ashrrev_i32_e32 v0, 31, v16
	s_waitcnt lgkmcnt(0)
	s_lshl_b64 s[64:65], s[62:63], 6
	v_ashrrev_i32_e32 v165, 31, v164
	v_lshl_add_u64 v[6:7], v[2:3], 0, s[56:57]
	v_lshrrev_b32_e32 v0, 28, v0
	v_lshl_add_u64 v[2:3], s[64:65], 0, v[164:165]
	v_add_u32_e32 v0, v16, v0
	v_lshlrev_b64 v[2:3], 11, v[2:3]
	v_ashrrev_i32_e32 v166, 4, v0
	v_lshl_add_u64 v[4:5], s[68:69], 0, v[2:3]
	v_lshlrev_b32_e32 v2, 3, v15
	v_ashrrev_i32_e32 v3, 31, v2
	v_ashrrev_i32_e32 v167, 31, v166
	v_and_b32_e32 v0, -16, v0
	v_lshl_add_u64 v[8:9], v[2:3], 1, v[4:5]
	v_lshl_add_u64 v[4:5], s[64:65], 0, v[166:167]
	v_sub_u32_e32 v17, v16, v0
	v_lshlrev_b64 v[4:5], 11, v[4:5]
	v_lshl_add_u64 v[10:11], s[68:69], 0, v[4:5]
	v_lshlrev_b32_e32 v4, 3, v17
	v_ashrrev_i32_e32 v5, 31, v4
	s_sub_i32 s56, s16, s95
	v_lshl_add_u64 v[10:11], v[4:5], 1, v[10:11]
	s_lshl_b64 s[64:65], s[62:63], 7
	v_lshlrev_b32_e32 v0, 3, v14
	global_load_dwordx4 v[112:115], v[8:9], off
	global_load_dwordx4 v[116:119], v[10:11], off
	s_add_u32 s64, s70, s64
	v_and_b32_e32 v0, 56, v0
	v_ashrrev_i32_e32 v10, 3, v14
	s_addc_u32 s65, s71, s65
	v_lshlrev_b32_e32 v0, 1, v0
	v_ashrrev_i32_e32 v11, 31, v10
	v_lshl_add_u64 v[8:9], s[64:65], 0, v[0:1]
	v_lshlrev_b64 v[168:169], 15, v[10:11]
	v_lshl_add_u64 v[12:13], v[8:9], 0, v[168:169]
	global_load_dwordx4 v[152:155], v[12:13], off
	v_ashrrev_i32_e32 v12, 3, v16
	v_bfe_u32 v183, v14, 5, 1
	v_ashrrev_i32_e32 v13, 31, v12
	v_lshlrev_b32_e32 v162, 4, v183
	v_lshlrev_b64 v[170:171], 15, v[12:13]
	v_mov_b32_e32 v163, v1
	v_lshl_add_u64 v[8:9], v[8:9], 0, v[170:171]
	v_lshl_add_u64 v[6:7], v[6:7], 0, v[162:163]
	global_load_dwordx4 v[156:159], v[8:9], off
	global_load_dwordx4 v[120:123], v[6:7], off
	global_load_dwordx4 v[124:127], v[6:7], off offset:32
	global_load_dwordx4 v[128:131], v[6:7], off offset:64
	global_load_dwordx4 v[132:135], v[6:7], off offset:96
	global_load_dwordx4 v[136:139], v[6:7], off offset:128
	global_load_dwordx4 v[140:143], v[6:7], off offset:160
	global_load_dwordx4 v[144:147], v[6:7], off offset:192
	global_load_dwordx4 v[148:151], v[6:7], off offset:224
	v_mul_lo_u32 v195, v164, s86
	v_lshlrev_b32_e32 v196, 4, v15
	v_mul_lo_u32 v197, v166, s86
	v_add3_u32 v6, 0, v195, v196
	v_lshlrev_b32_e32 v198, 4, v17
	v_add3_u32 v7, 0, v197, v198
	v_readfirstlane_b32 s16, v14
	v_mul_lo_u32 v200, v10, s87
	s_cmpk_gt_i32 s16, 0xff
	v_mul_lo_u32 v201, v12, s87
	s_cselect_b64 s[64:65], -1, 0
	s_cmpk_lt_i32 s16, 0x100
	v_and_b32_e32 v163, 31, v14
	s_cselect_b64 s[66:67], -1, 0
	s_cmp_lt_i32 s56, 1
	s_mov_b32 s63, 0
	s_waitcnt vmcnt(11)
	ds_write_b128 v6, v[112:115]
	s_waitcnt vmcnt(10)
	ds_write_b128 v7, v[116:119]
	v_lshlrev_b32_e32 v6, 4, v14
	v_and_b32_e32 v6, 0x70, v6
	v_add_u32_e32 v199, 0, v6
	v_add_u32_e32 v6, v199, v200
	s_waitcnt vmcnt(9)
	ds_write_b128 v6, v[152:155] offset:34816
	v_add_u32_e32 v6, v199, v201
	s_waitcnt vmcnt(8)
	ds_write_b128 v6, v[156:159] offset:34816
	s_waitcnt lgkmcnt(0)
	s_barrier
	s_cbranch_scc1 .LBB0_505
	s_add_i32 s16, s75, -4
	s_min_i32 s16, s16, s72
	s_cmp_gt_i32 s75, 3
	s_cselect_b32 s92, s16, 0
	s_add_i32 s16, s84, s95
	v_lshlrev_b32_e32 v6, 2, v183
	s_sub_i32 s16, s16, s74
	v_lshl_add_u64 v[172:173], s[70:71], 0, v[0:1]
	v_lshl_add_u32 v0, v183, 4, 0
	v_sub_u32_e32 v7, v6, v178
	v_sub_u32_e32 v6, v6, v179
	s_mulk_i32 s16, 0x7c
	v_mov_b32_e32 v14, v1
	v_mov_b32_e32 v15, v1
	s_add_i32 s92, s92, s73
	v_add_u32_e32 v210, 15, v7
	v_add_u32_e32 v211, 8, v6
	v_lshl_add_u64 v[174:175], v[2:3], 1, s[68:69]
	v_lshl_add_u64 v[176:177], v[4:5], 1, s[68:69]
	v_mad_u32_u24 v212, v163, s87, v0
	v_mad_u32_u24 v213, v163, s86, v0
	s_add_i32 s16, s16, 0
	v_mov_b32_e32 v0, v1
	v_mov_b32_e32 v2, v1
	v_mov_b32_e32 v3, v1
	v_mov_b32_e32 v4, v1
	v_mov_b32_e32 v5, v1
	v_mov_b32_e32 v6, v1
	v_mov_b32_e32 v7, v1
	v_mov_b32_e32 v8, v1
	v_mov_b32_e32 v9, v1
	v_mov_b32_e32 v10, v1
	v_mov_b32_e32 v11, v1
	v_mov_b32_e32 v12, v1
	v_mov_b32_e32 v13, v1
	v_mov_b64_e32 v[78:79], v[14:15]
	v_mov_b64_e32 v[62:63], v[14:15]
	v_mov_b64_e32 v[46:47], v[14:15]
	v_mov_b64_e32 v[30:31], v[14:15]
	s_add_i32 s93, s92, 8
	s_mov_b32 s94, 1
	s_add_i32 s95, s16, 0x16364
	s_mov_b64 s[68:69], 0
	v_mov_b32_e32 v194, 0
	v_mov_b32_e32 v214, 0xf149f2ca
	v_mov_b32_e32 v92, 0
	v_mov_b32_e32 v93, 0
	v_mov_b32_e32 v94, 0
	v_mov_b32_e32 v95, 0
	v_mov_b32_e32 v88, 0
	v_mov_b32_e32 v89, 0
	v_mov_b32_e32 v90, 0
	v_mov_b32_e32 v91, 0
	v_mov_b32_e32 v84, 0
	v_mov_b32_e32 v85, 0
	v_mov_b32_e32 v86, 0
	v_mov_b32_e32 v87, 0
	v_mov_b32_e32 v80, 0
	v_mov_b32_e32 v81, 0
	v_mov_b32_e32 v82, 0
	v_mov_b32_e32 v83, 0
	v_mov_b64_e32 v[76:77], v[12:13]
	v_mov_b64_e32 v[74:75], v[10:11]
	v_mov_b64_e32 v[72:73], v[8:9]
	v_mov_b64_e32 v[70:71], v[6:7]
	v_mov_b64_e32 v[68:69], v[4:5]
	v_mov_b64_e32 v[66:67], v[2:3]
	v_mov_b64_e32 v[64:65], v[0:1]
	v_mov_b64_e32 v[60:61], v[12:13]
	v_mov_b64_e32 v[58:59], v[10:11]
	v_mov_b64_e32 v[56:57], v[8:9]
	v_mov_b64_e32 v[54:55], v[6:7]
	v_mov_b64_e32 v[52:53], v[4:5]
	v_mov_b64_e32 v[50:51], v[2:3]
	v_mov_b64_e32 v[48:49], v[0:1]
	v_mov_b64_e32 v[44:45], v[12:13]
	v_mov_b64_e32 v[42:43], v[10:11]
	v_mov_b64_e32 v[40:41], v[8:9]
	v_mov_b64_e32 v[38:39], v[6:7]
	v_mov_b64_e32 v[36:37], v[4:5]
	v_mov_b64_e32 v[34:35], v[2:3]
	v_mov_b64_e32 v[32:33], v[0:1]
	v_mov_b64_e32 v[28:29], v[12:13]
	v_mov_b64_e32 v[26:27], v[10:11]
	v_mov_b64_e32 v[24:25], v[8:9]
	v_mov_b64_e32 v[22:23], v[6:7]
	v_mov_b64_e32 v[20:21], v[4:5]
	v_mov_b64_e32 v[18:19], v[2:3]
	v_mov_b64_e32 v[16:17], v[0:1]
	s_mov_b32 s96, 0
	s_waitcnt vmcnt(0)
	s_branch .LBB0_484

; #define LAS __attribute__((address_space(3)))
; template <int DQK, int MODE> ...
;     ...
;         if (tile >= wlo && tile < whi) {
;             const LAS unsigned char* kb = lds + buf * G::KBUF;
;             f32x16 S0, S1;
; #pragma unroll
;             for (int j = 0; j < 16; ++j) { S0[j] = 0.f; S1[j] = 0.f; }
; #pragma unroll
;             for (int dc = 0; dc < DQK / 16; ++dc) {
;                 const bf16x8 ka = *(const LAS bf16x8*)(kb + r32 * G::KROW + dc * 32 + hh * 16);
;                 const bf16x8 kb2 = *(const LAS bf16x8*)(kb + (32 + r32) * G::KROW + dc * 32 + hh * 16);
;                 S0 = __builtin_amdgcn_mfma_f32_32x32x16_bf16(ka, qf[dc], S0, 0, 0, 0);
;                 S1 = __builtin_amdgcn_mfma_f32_32x32x16_bf16(kb2, qf[dc], S1, 0, 0, 0);
;             }
;             if (MODE == 1) {
;                 const LAS float* rpbL = (const LAS float*)(lds + G::RPB_OFF);
;                 const int c = a0; int cs = c - 8; cs = cs < 0 ? 0 : (cs > 48 ? 48 : cs);
;                 const LAS float* rrow = rpbL + (tile + a1) * 31;
;                 int cb = 4 * hh + 15 - c, vb_ = 4 * hh - cs; asm volatile("" : "+v"(cb), "+v"(vb_));
;                 float bb0[16], bb1[16];
; #pragma unroll
;                 for (int j = 0; j < 16; ++j) {
;                     const int kk = (j & 3) + 8 * (j >> 2);
;                     int i0 = kk + cb; i0 = i0 < 0 ? 0 : (i0 > 30 ? 30 : i0); int i1 = kk + 32 + cb; i1 = i1 < 0 ? 0 : (i1 > 30 ? 30 : i1);
;                     bb0[j] = rrow[i0]; bb1[j] = rrow[i1];
;                 }
.LBB0_488:
	s_add_i32 s16, s94, -1
	s_add_i32 s17, s74, -1
	s_and_b32 s74, s16, 1
	s_cmp_lt_i32 s17, s92
	s_cselect_b64 vcc, -1, 0
	s_cmp_ge_i32 s17, s93
	s_cselect_b64 s[16:17], -1, 0
	s_or_b64 s[16:17], vcc, s[16:17]
	s_and_b64 vcc, exec, s[16:17]
	s_cbranch_vccnz .LBB0_495
	s_mul_i32 s16, s74, 0x4400
	v_add_u32_e32 v0, s16, v213
	ds_read_b128 v[2:5], v0
	ds_read_b128 v[6:9], v0 offset:32
	ds_read_b128 v[10:13], v0 offset:8704
	ds_read_b128 v[216:219], v0 offset:8736
	ds_read_b128 v[96:99], v0 offset:64
	ds_read_b128 v[100:103], v0 offset:96
	v_mov_b32_e32 v14, v210
	v_mov_b32_e32 v215, v211
	s_waitcnt lgkmcnt(5)
	v_mfma_f32_32x32x16_bf16 v[80:95], v[2:5], v[120:123], 0
	ds_read_b128 v[2:5], v0 offset:8768
	ds_read_b128 v[220:223], v0 offset:8800
	ds_read_b128 v[104:107], v0 offset:128
	ds_read_b128 v[108:111], v0 offset:160
	ds_read_b128 v[224:227], v0 offset:8832
	ds_read_b128 v[228:231], v0 offset:8864
	ds_read_b128 v[232:235], v0 offset:192
	ds_read_b128 v[236:239], v0 offset:224
	s_waitcnt lgkmcnt(12)
	v_mfma_f32_32x32x16_bf16 v[80:95], v[6:9], v[124:127], v[80:95]
	ds_read_b128 v[6:9], v0 offset:8896
	ds_read_b128 v[240:243], v0 offset:8928
	s_nop 0
	v_add_u32_e32 v245, 33, v14
	v_max_i32_e32 v244, -1, v14
	v_max_i32_e32 v246, -8, v14
	v_max_i32_e32 v248, -9, v14
	s_waitcnt lgkmcnt(11)
	v_mfma_f32_32x32x16_bf16 v[80:95], v[96:99], v[128:131], v[80:95]
	v_max_i32_e32 v96, -2, v14
	v_add_u32_e32 v96, 2, v96
	v_min_u32_e32 v96, 30, v96
	v_add_u32_e32 v97, 34, v14
	v_max_i32_e32 v98, -3, v14
	v_med3_i32 v97, v97, 0, 30
	v_add_u32_e32 v98, 3, v98
	s_waitcnt lgkmcnt(10)
	v_mfma_f32_32x32x16_bf16 v[80:95], v[100:103], v[132:135], v[80:95]
	v_med3_i32 v102, v245, 0, 30
	v_lshl_add_u32 v245, v97, 2, s95
	v_min_u32_e32 v97, 30, v98
	v_add_u32_e32 v99, 35, v14
	v_add_u32_e32 v247, 40, v14
	v_add_u32_e32 v100, 41, v14
	v_add_u32_e32 v101, 1, v244
	s_waitcnt lgkmcnt(7)
	v_mfma_f32_32x32x16_bf16 v[80:95], v[104:107], v[136:139], v[80:95]
	v_med3_i32 v99, v99, 0, 30
	v_add_u32_e32 v103, 8, v246
	v_add_u32_e32 v105, 9, v248
	v_med3_i32 v104, v247, 0, 30
	v_med3_i32 v100, v100, 0, 30
	v_min_u32_e32 v101, 30, v101
	v_lshl_add_u32 v246, v99, 2, s95
	s_waitcnt lgkmcnt(6)
	v_mfma_f32_32x32x16_bf16 v[80:95], v[108:111], v[140:143], v[80:95]
	v_min_u32_e32 v98, 30, v103
	v_min_u32_e32 v99, 30, v105
	v_lshl_add_u32 v244, v102, 2, s95
	v_lshl_add_u32 v247, v98, 2, s95
	v_lshl_add_u32 v248, v99, 2, s95
	v_add_u32_e32 v0, 32, v14
	v_med3_i32 v15, v14, 0, 30
	s_waitcnt lgkmcnt(3)
	v_mfma_f32_32x32x16_bf16 v[80:95], v[232:235], v[144:147], v[80:95]
	v_lshl_add_u32 v234, v96, 2, s95
	v_max_i32_e32 v96, -10, v14
	v_add_u32_e32 v96, 10, v96
	v_min_u32_e32 v96, 30, v96
	v_lshl_add_u32 v235, v97, 2, s95
	v_add_u32_e32 v97, 42, v14
	v_med3_i32 v97, v97, 0, 30
	s_waitcnt lgkmcnt(2)
	v_mfma_f32_32x32x16_bf16 v[80:95], v[236:239], v[148:151], v[80:95]
	v_lshl_add_u32 v237, v96, 2, s95
	v_max_i32_e32 v96, -11, v14
	v_add_u32_e32 v96, 11, v96
	v_lshl_add_u32 v238, v97, 2, s95
	v_min_u32_e32 v96, 30, v96
	v_add_u32_e32 v97, 43, v14
	v_med3_i32 v97, v97, 0, 30
	v_lshl_add_u32 v239, v96, 2, s95
	v_max_i32_e32 v96, -16, v14
	v_lshl_add_u32 v249, v97, 2, s95
	v_add_u32_e32 v96, 16, v96
	v_add_u32_e32 v97, 48, v14
	v_min_u32_e32 v96, 30, v96
	v_med3_i32 v97, v97, 0, 30
	v_lshl_add_u32 v232, v104, 2, s95
	v_lshl_add_u32 v233, v101, 2, s95
	v_lshl_add_u32 v236, v100, 2, s95
	v_lshl_add_u32 v250, v96, 2, s95
	v_lshl_add_u32 v251, v97, 2, s95
	v_mfma_f32_32x32x16_bf16 v[96:111], v[10:13], v[120:123], 0
	v_max_i32_e32 v10, 0xffffffef, v14
	v_add_u32_e32 v10, 17, v10
	v_max_i32_e32 v12, 0xffffffee, v14
	v_min_u32_e32 v10, 30, v10
	v_add_u32_e32 v11, 49, v14
	v_add_u32_e32 v12, 18, v12
	v_add_u32_e32 v13, 50, v14
	v_mfma_f32_32x32x16_bf16 v[96:111], v[216:219], v[124:127], v[96:111]
	v_max_i32_e32 v216, 0xffffffe7, v14
	v_max_i32_e32 v218, 0xffffffe6, v14
	v_add_u32_e32 v216, 25, v216
	v_add_u32_e32 v217, 57, v14
	v_add_u32_e32 v218, 26, v218
	v_add_u32_e32 v219, 58, v14
	v_min_u32_e32 v216, 30, v216
	v_mfma_f32_32x32x16_bf16 v[96:111], v[2:5], v[128:131], v[96:111]
	v_max_i32_e32 v2, 0xffffffed, v14
	v_max_i32_e32 v4, 0xffffffe8, v14
	v_add_u32_e32 v2, 19, v2
	v_add_u32_e32 v3, 51, v14
	v_add_u32_e32 v4, 24, v4
	v_add_u32_e32 v5, 56, v14
	v_med3_i32 v217, v217, 0, 30
	v_mfma_f32_32x32x16_bf16 v[96:111], v[220:223], v[132:135], v[96:111]
	v_min_u32_e32 v218, 30, v218
	v_med3_i32 v219, v219, 0, 30
	v_med3_i32 v0, v0, 0, 30
	v_lshl_add_u32 v15, v15, 2, s95
	v_med3_i32 v11, v11, 0, 30
	v_lshl_add_u32 v10, v10, 2, s95
	v_min_u32_e32 v12, 30, v12
	v_mfma_f32_32x32x16_bf16 v[96:111], v[224:227], v[136:139], v[96:111]
	v_med3_i32 v13, v13, 0, 30
	v_min_u32_e32 v2, 30, v2
	v_med3_i32 v3, v3, 0, 30
	v_min_u32_e32 v4, 30, v4
	v_med3_i32 v5, v5, 0, 30
	v_lshl_add_u32 v216, v216, 2, s95
	v_lshl_add_u32 v217, v217, 2, s95
	v_mfma_f32_32x32x16_bf16 v[96:111], v[228:231], v[140:143], v[96:111]
	v_lshl_add_u32 v218, v218, 2, s95
	v_lshl_add_u32 v219, v219, 2, s95
	v_lshl_add_u32 v0, v0, 2, s95
	v_lshl_add_u32 v11, v11, 2, s95
	v_lshl_add_u32 v12, v12, 2, s95
	v_lshl_add_u32 v13, v13, 2, s95
	v_lshl_add_u32 v2, v2, 2, s95
	s_waitcnt lgkmcnt(1)
	v_mfma_f32_32x32x16_bf16 v[96:111], v[6:9], v[144:147], v[96:111]
	v_max_i32_e32 v6, 0xffffffe5, v14
	v_add_u32_e32 v6, 27, v6
	v_add_u32_e32 v7, 59, v14
	v_min_u32_e32 v6, 30, v6
	v_med3_i32 v7, v7, 0, 30
	v_lshl_add_u32 v3, v3, 2, s95
	v_lshl_add_u32 v4, v4, 2, s95
	s_waitcnt lgkmcnt(0)
; __device__ __forceinline__ int crow(int r, int hi) { return (r & 3) + 8 * (r >> 2) + 4 * hi; }
; template <int DQK, int MODE> ...
;     ...
; #pragma unroll
;                 for (int j = 0; j < 16; ++j) {
;                     const int kk = (j & 3) + 8 * (j >> 2);
;                     int i0 = kk + cb; i0 = i0 < 0 ? 0 : (i0 > 30 ? 30 : i0); int i1 = kk + 32 + cb; i1 = i1 < 0 ? 0 : (i1 > 30 ? 30 : i1);
;                     bb0[j] = rrow[i0]; bb1[j] = rrow[i1];
;                 }
; #pragma unroll
;                 for (int j = 0; j < 16; ++j) asm volatile("" : "+v"(bb0[j]), "+v"(bb1[j]));
; #pragma unroll
;                 for (int j = 0; j < 16; ++j) {
;                     const int kk = (j & 3) + 8 * (j >> 2);
;                     S0[j] = ((unsigned)(kk + vb_) < 16u) ? S0[j] + bb0[j] : -INFINITY;
;                     S1[j] = ((unsigned)(kk + 32 + vb_) < 16u) ? S1[j] + bb1[j] : -INFINITY;
;                 }
;             }
;             if (MODE == 2) {
;                 const int dbase = tile * 64 - a0;
; #pragma unroll
;                 for (int j = 0; j < 16; ++j) {
;                     const int d0 = dbase + crow(j, hh), d1 = d0 + 32;
;                     S0[j] = (d0 >= -128 && d0 <= 128) ? S0[j] : -INFINITY;
;                     S1[j] = (d1 >= -128 && d1 <= 128) ? S1[j] : -INFINITY;
;                 }
;             }
;             float pmax = S0[0];
; #pragma unroll
;             for (int j = 1; j < 16; ++j) pmax = fmaxf(pmax, S0[j]);
; #pragma unroll
;             for (int j = 0; j < 16; ++j) pmax = fmaxf(pmax, S1[j]);
;             { auto rr = __builtin_amdgcn_permlane32_swap(__float_as_uint(pmax), __float_as_uint(pmax), false, false); pmax = fmaxf(__uint_as_float(rr[0]), __uint_as_float(rr[1])); }
;             if (!__all(pmax - m <= 8.0f)) {
	v_mfma_f32_32x32x16_bf16 v[96:111], v[240:243], v[148:151], v[96:111]
	v_lshl_add_u32 v5, v5, 2, s95
	v_lshl_add_u32 v6, v6, 2, s95
	v_lshl_add_u32 v7, v7, 2, s95
	ds_read_b32 v8, v15
	ds_read_b32 v9, v0
	ds_read_b32 v14, v244
	ds_read_b32 v15, v245
	ds_read_b32 v220, v246
	ds_read_b32 v221, v235
	ds_read_b32 v222, v234
	ds_read_b32 v223, v233
	ds_read_b32 v224, v232
	ds_read_b32 v225, v236
	ds_read_b32 v226, v238
	ds_read_b32 v227, v249
	ds_read_b32 v228, v239
	ds_read_b32 v229, v237
	ds_read_b32 v230, v248
	ds_read_b32 v231, v247
	ds_read_b32 v232, v251
	ds_read_b32 v233, v11
	ds_read_b32 v234, v13
	ds_read_b32 v235, v3
	ds_read_b32 v236, v2
	ds_read_b32 v237, v12
	ds_read_b32 v10, v10
	ds_read_b32 v238, v250
	ds_read_b32 v239, v5
	ds_read_b32 v217, v217
	ds_read_b32 v219, v219
	ds_read_b32 v240, v7
	ds_read_b32 v241, v6
	ds_read_b32 v218, v218
	ds_read_b32 v216, v216
	ds_read_b32 v242, v4
	s_waitcnt lgkmcnt(14)
	v_cmp_gt_u32_e32 vcc, 16, v215
	v_add_f32_e32 v0, v80, v8
	v_and_b32_e32 v243, -16, v215
	v_cndmask_b32_e32 v0, v193, v0, vcc
	v_add_f32_e32 v2, v96, v9
	v_cmp_eq_u32_e32 vcc, s89, v243
	v_add_u32_e32 v3, 1, v215
	s_nop 0
	v_cndmask_b32_e32 v2, v193, v2, vcc
	v_add_f32_e32 v4, v81, v223
	v_cmp_gt_u32_e32 vcc, 16, v3
	v_add_f32_e32 v5, v97, v14
	v_add_f32_e32 v6, v82, v222
	v_cndmask_b32_e32 v3, v193, v4, vcc
	v_add_u32_e32 v4, 33, v215
	v_cmp_gt_u32_e32 vcc, 16, v4
	v_add_f32_e32 v7, v98, v15
	v_add_f32_e32 v8, v83, v221
	v_cndmask_b32_e32 v4, v193, v5, vcc
	v_add_u32_e32 v5, 2, v215
	v_cmp_gt_u32_e32 vcc, 16, v5
	v_add_f32_e32 v9, v99, v220
	v_add_f32_e32 v11, v84, v231
	v_cndmask_b32_e32 v5, v193, v6, vcc
	v_add_u32_e32 v6, 34, v215
	v_cmp_gt_u32_e32 vcc, 16, v6
	v_add_f32_e32 v12, v100, v224
	s_waitcnt lgkmcnt(8)
	v_cndmask_b32_e32 v6, v193, v7, vcc
	v_add_u32_e32 v7, 3, v215
	v_cmp_gt_u32_e32 vcc, 16, v7
	v_add_f32_e32 v13, v85, v230
	v_add_f32_e32 v14, v101, v225
	v_cndmask_b32_e32 v7, v193, v8, vcc
	v_add_u32_e32 v8, 35, v215
	v_cmp_gt_u32_e32 vcc, 16, v8
	v_add_f32_e32 v15, v86, v229
	v_add_f32_e32 v80, v102, v226
	v_cndmask_b32_e32 v8, v193, v9, vcc
	v_add_u32_e32 v9, 8, v215
	v_cmp_gt_u32_e32 vcc, 16, v9
	v_add_f32_e32 v81, v87, v228
	v_add_f32_e32 v82, v103, v227
	v_cndmask_b32_e32 v9, v193, v11, vcc
	v_add_u32_e32 v11, 40, v215
	v_cmp_gt_u32_e32 vcc, 16, v11
	s_waitcnt lgkmcnt(0)
	s_nop 0
	v_cndmask_b32_e32 v11, v193, v12, vcc
	v_add_u32_e32 v12, 9, v215
	v_cmp_gt_u32_e32 vcc, 16, v12
	v_add_f32_e32 v10, v89, v10
	s_nop 0
	v_cndmask_b32_e32 v12, v193, v13, vcc
	v_add_u32_e32 v13, 41, v215
	v_cmp_gt_u32_e32 vcc, 16, v13
	s_nop 1
	v_cndmask_b32_e32 v13, v193, v14, vcc
	v_add_u32_e32 v14, 10, v215
	v_cmp_gt_u32_e32 vcc, 16, v14
	v_add_u32_e32 v14, 42, v215
	s_nop 0
	v_cndmask_b32_e32 v15, v193, v15, vcc
	v_cmp_gt_u32_e32 vcc, 16, v14
	v_add_u32_e32 v14, 11, v215
	s_nop 0
	v_cndmask_b32_e32 v80, v193, v80, vcc
	v_cmp_gt_u32_e32 vcc, 16, v14
	v_add_u32_e32 v14, 43, v215
	s_nop 0
	v_cndmask_b32_e32 v81, v193, v81, vcc
	v_cmp_gt_u32_e32 vcc, 16, v14
	v_add_f32_e32 v14, v88, v238
	s_nop 0
	v_cndmask_b32_e32 v82, v193, v82, vcc
	v_cmp_lt_u32_e32 vcc, s88, v215
	s_nop 1
	v_cndmask_b32_e32 v83, v193, v14, vcc
	v_add_f32_e32 v14, v104, v232
	v_cmp_eq_u32_e32 vcc, s85, v243
	s_nop 1
	v_cndmask_b32_e32 v84, v193, v14, vcc
	v_add_u32_e32 v14, 17, v215
	v_cmp_gt_u32_e32 vcc, 16, v14
	v_add_f32_e32 v14, v105, v233
	s_nop 0
	v_cndmask_b32_e32 v85, v193, v10, vcc
	v_add_u32_e32 v10, 49, v215
	v_cmp_gt_u32_e32 vcc, 16, v10
	v_add_u32_e32 v10, 18, v215
	s_nop 0
	v_cndmask_b32_e32 v86, v193, v14, vcc
	v_add_f32_e32 v14, v90, v237
	v_cmp_gt_u32_e32 vcc, 16, v10
	v_add_u32_e32 v10, 50, v215
	s_nop 0
	v_cndmask_b32_e32 v87, v193, v14, vcc
	v_add_f32_e32 v14, v106, v234
	v_cmp_gt_u32_e32 vcc, 16, v10
	v_add_u32_e32 v10, 19, v215
	s_nop 0
	v_cndmask_b32_e32 v88, v193, v14, vcc
	v_add_f32_e32 v14, v91, v236
	v_cmp_gt_u32_e32 vcc, 16, v10
	v_add_u32_e32 v10, 51, v215
	s_nop 0
	v_cndmask_b32_e32 v89, v193, v14, vcc
	v_add_f32_e32 v14, v107, v235
	v_cmp_gt_u32_e32 vcc, 16, v10
	v_add_u32_e32 v10, 24, v215
	s_nop 0
	v_cndmask_b32_e32 v90, v193, v14, vcc
	v_add_f32_e32 v14, v92, v242
	v_cmp_gt_u32_e32 vcc, 16, v10
	v_add_u32_e32 v10, 56, v215
	s_nop 0
	v_cndmask_b32_e32 v91, v193, v14, vcc
	v_add_f32_e32 v14, v108, v239
	v_cmp_gt_u32_e32 vcc, 16, v10
	v_add_u32_e32 v10, 25, v215
	s_nop 0
	v_cndmask_b32_e32 v92, v193, v14, vcc
	v_add_f32_e32 v14, v93, v216
	v_cmp_gt_u32_e32 vcc, 16, v10
	v_add_u32_e32 v10, 57, v215
	s_nop 0
	v_cndmask_b32_e32 v93, v193, v14, vcc
	v_add_f32_e32 v14, v109, v217
	v_cmp_gt_u32_e32 vcc, 16, v10
	v_add_u32_e32 v10, 26, v215
	s_nop 0
	v_cndmask_b32_e32 v97, v193, v14, vcc
	v_add_f32_e32 v14, v94, v218
	v_cmp_gt_u32_e32 vcc, 16, v10
	v_add_u32_e32 v10, 58, v215
	s_nop 0
	v_cndmask_b32_e32 v94, v193, v14, vcc
	v_add_f32_e32 v14, v110, v219
	v_cmp_gt_u32_e32 vcc, 16, v10
	v_add_u32_e32 v10, 27, v215
	s_nop 0
	v_cndmask_b32_e32 v99, v193, v14, vcc
	v_add_f32_e32 v14, v95, v241
	v_cmp_gt_u32_e32 vcc, 16, v10
	v_add_u32_e32 v10, 59, v215
	s_nop 0
	v_cndmask_b32_e32 v95, v193, v14, vcc
	v_cmp_gt_u32_e32 vcc, 16, v10
	v_max_f32_e32 v10, v0, v3
	v_max3_f32 v10, v10, v5, v7
	v_max3_f32 v10, v10, v9, v12
	v_max3_f32 v10, v10, v15, v81
	v_max3_f32 v10, v10, v83, v85
	v_max3_f32 v10, v10, v87, v89
	v_max3_f32 v10, v10, v91, v93
	v_max3_f32 v10, v10, v94, v95
	v_max3_f32 v10, v10, v2, v4
	v_max3_f32 v10, v10, v6, v8
	v_max3_f32 v10, v10, v11, v13
	v_max3_f32 v10, v10, v80, v82
	v_max3_f32 v10, v10, v84, v86
	v_add_f32_e32 v14, v111, v240
	v_max3_f32 v10, v10, v88, v90
	v_cndmask_b32_e32 v101, v193, v14, vcc
	v_max3_f32 v10, v10, v92, v97
	v_max3_f32 v10, v10, v99, v101
	v_mov_b32_e32 v14, v10
	s_nop 1
	v_permlane32_swap_b32_e32 v10, v14
	v_max_f32_e32 v14, v14, v14
	v_max_f32_e32 v10, v10, v10
	v_max_f32_e32 v10, v10, v14
	v_sub_f32_e32 v14, v10, v214
	v_cmp_ge_f32_e32 vcc, s90, v14
	s_cmp_eq_u64 vcc, exec
	s_cbranch_scc1 .LBB0_491
; template <int DQK, int MODE> ...
;     ...
;             if (!__all(pmax - m <= 8.0f)) {
;                 const float mn2 = fmaxf(m, pmax); const float alpha = __builtin_amdgcn_exp2f(m - mn2); m = mn2; l *= alpha;
; #pragma unroll
;                 for (int i = 0; i < 4; ++i)
; #pragma unroll
;                     for (int j = 0; j < 16; ++j) O[i][j] *= alpha;
;             }
	v_max_f32_e32 v10, v10, v10
	v_max_f32_e32 v14, v214, v214
	v_max_f32_e32 v14, v14, v10
	v_sub_f32_e32 v10, v214, v14
	v_exp_f32_e32 v10, v10
	v_mov_b32_e32 v214, v14
	v_pk_mul_f32 v[78:79], v[78:79], v[10:11] op_sel_hi:[1,0]
	v_pk_mul_f32 v[76:77], v[76:77], v[10:11] op_sel_hi:[1,0]
	v_pk_mul_f32 v[74:75], v[74:75], v[10:11] op_sel_hi:[1,0]
	v_pk_mul_f32 v[72:73], v[72:73], v[10:11] op_sel_hi:[1,0]
	v_pk_mul_f32 v[70:71], v[70:71], v[10:11] op_sel_hi:[1,0]
	v_pk_mul_f32 v[68:69], v[68:69], v[10:11] op_sel_hi:[1,0]
	v_pk_mul_f32 v[66:67], v[66:67], v[10:11] op_sel_hi:[1,0]
	v_pk_mul_f32 v[64:65], v[64:65], v[10:11] op_sel_hi:[1,0]
	v_pk_mul_f32 v[62:63], v[62:63], v[10:11] op_sel_hi:[1,0]
	v_pk_mul_f32 v[60:61], v[60:61], v[10:11] op_sel_hi:[1,0]
	v_pk_mul_f32 v[58:59], v[58:59], v[10:11] op_sel_hi:[1,0]
	v_pk_mul_f32 v[56:57], v[56:57], v[10:11] op_sel_hi:[1,0]
	v_pk_mul_f32 v[54:55], v[54:55], v[10:11] op_sel_hi:[1,0]
	v_pk_mul_f32 v[52:53], v[52:53], v[10:11] op_sel_hi:[1,0]
	v_pk_mul_f32 v[50:51], v[50:51], v[10:11] op_sel_hi:[1,0]
	v_pk_mul_f32 v[48:49], v[48:49], v[10:11] op_sel_hi:[1,0]
	v_pk_mul_f32 v[46:47], v[46:47], v[10:11] op_sel_hi:[1,0]
	v_pk_mul_f32 v[44:45], v[44:45], v[10:11] op_sel_hi:[1,0]
	v_pk_mul_f32 v[42:43], v[42:43], v[10:11] op_sel_hi:[1,0]
	v_pk_mul_f32 v[40:41], v[40:41], v[10:11] op_sel_hi:[1,0]
	v_pk_mul_f32 v[38:39], v[38:39], v[10:11] op_sel_hi:[1,0]
	v_pk_mul_f32 v[36:37], v[36:37], v[10:11] op_sel_hi:[1,0]
	v_pk_mul_f32 v[34:35], v[34:35], v[10:11] op_sel_hi:[1,0]
	v_pk_mul_f32 v[32:33], v[32:33], v[10:11] op_sel_hi:[1,0]
	v_pk_mul_f32 v[30:31], v[30:31], v[10:11] op_sel_hi:[1,0]
	v_pk_mul_f32 v[28:29], v[28:29], v[10:11] op_sel_hi:[1,0]
	v_pk_mul_f32 v[26:27], v[26:27], v[10:11] op_sel_hi:[1,0]
	v_pk_mul_f32 v[24:25], v[24:25], v[10:11] op_sel_hi:[1,0]
	v_pk_mul_f32 v[22:23], v[22:23], v[10:11] op_sel_hi:[1,0]
	v_pk_mul_f32 v[20:21], v[20:21], v[10:11] op_sel_hi:[1,0]
	v_pk_mul_f32 v[18:19], v[18:19], v[10:11] op_sel_hi:[1,0]
	v_pk_mul_f32 v[16:17], v[16:17], v[10:11] op_sel_hi:[1,0]
	v_mul_f32_e32 v194, v194, v10

; #define ATT_LOAD(tile) do { const size_t key0 = (size_t)(tile) * 64; \
;         _Pragma("unroll") for (int i = 0; i < G::KC; ++i) kreg[i] = *(const u32x4*)(kbase + (key0 + krow_[i]) * kstride + kcc_[i] * 8); \
;         _Pragma("unroll") for (int i = 0; i < 2; ++i) { const int cid = tid + i * 512; vreg[i] = *(const u32x4*)(vtbase + (size_t)(cid >> 3) * M + key0 + (cid & 7) * 8); } } while (0)
; template <int DQK, int MODE> ...
;     ...
;     bf16x8 qf[DQK / 16];
; #pragma unroll
;     for (int dc = 0; dc < DQK / 16; ++dc) qf[dc] = *(const bf16x8*)(qptr + dc * 16 + hh * 8);
;     f32x16 O[4];
; #pragma unroll
;     for (int i = 0; i < 4; ++i)
; #pragma unroll
;         for (int j = 0; j < 16; ++j) O[i][j] = 0.f;
;     float m = m_init, l = l_init;
;     const int nt = tile_hi - tile_lo;
;     u32x4 kreg[G::KC], vreg[2];
;     int krow_[G::KC], kcc_[G::KC];
; #pragma unroll
;     for (int i = 0; i < G::KC; ++i) { const int cid = tid + i * 512; krow_[i] = cid / (DQK / 8); kcc_[i] = cid % (DQK / 8); }
;     ...
;     const bool late = __builtin_amdgcn_readfirstlane(tid >> 6) >= 4;
;     bf16x8 pf[4]; bool have_pf = false; int vprev = 0;
; #pragma unroll
;     for (int i = 0; i < 4; ++i) pf[i] = (bf16x8){0, 0, 0, 0, 0, 0, 0, 0};
;     ATT_LOAD(tile_lo); ATT_WRITE(0, 0);
;     __syncthreads();
; __global__ void __launch_bounds__(NTHREADS, 2) fwd_megakernel(Params P) {
;     ...
;                     int kvh = u & 3, ch = u >> 2;
;                     if (G == 256) { const int b = u & 255, x = b & 7, j = b >> 3; kvh = u >> 8; ch = 32 * x + j; }
;                     const int tok0 = ch * 64;
;                     const int seqbase = tok0 < 8192 ? (tok0 & ~4095) : (tok0 & ~2047); const int T = tok0 < 8192 ? 4096 : 2048;
;                     const int head = kvh * 4 + (wave >> 1);
;                     const int tq = tok0 + (wave & 1) * 32 + (lane & 31);
;                     int tlo = ch - 2, thi = ch + 3; const int s0 = seqbase >> 6, s1 = (seqbase + T) >> 6; tlo = tlo < s0 ? s0 : tlo; thi = thi > s1 ? s1 : thi;
;                     const float sink = kp->in[I_SINKS][head] * LOG2E;
;                     attn_unit<128, 2>(lds, SQ + (size_t)tq * 2048 + head * 128, SK + kvh * 128, 512, SVT + (size_t)(kvh * 128) * M, tlo, thi, tlo, thi, tq, 0, sink, lane < 32 ? 1.f : 0.f,
.LBB0_1114:
	s_lshl_b32 s47, s60, 5
	s_bfe_u32 s46, s60, 0x50003
	s_and_b32 s47, s47, 0xe0
	s_and_b32 s33, s60, 3
	s_ashr_i32 s36, s60, 2
	s_ashr_i32 s48, s60, 8
	s_or_b32 s49, s47, s46
	s_and_b64 s[46:47], s[30:31], exec
	s_cselect_b32 s57, s49, s36
	s_cselect_b32 s33, s48, s33
	s_lshl_b32 s75, s57, 6
	s_cmpk_lt_i32 s57, 0x80
	s_cselect_b32 s36, s68, 0xfffff800
	s_load_dwordx2 s[50:51], s[6:7], 0xd8
	s_cselect_b32 s47, s69, 0x800
	s_and_b32 s36, s36, s75
	s_lshl_b32 s46, s33, 2
	s_add_i32 s46, s46, s67
	s_ashr_i32 s56, s36, 6
	s_add_i32 s36, s36, s47
	s_add_i32 s48, s57, -2
	s_add_i32 s49, s57, 3
	s_ashr_i32 s36, s36, 6
	s_ashr_i32 s47, s46, 31
	s_max_i32 s48, s48, s56
	s_min_i32 s36, s49, s36
	s_lshl_b64 s[52:53], s[46:47], 2
	s_waitcnt lgkmcnt(0)
	s_add_u32 s50, s50, s52
	s_addc_u32 s51, s51, s53
	s_lshl_b32 s54, s33, 7
	s_lshl_b32 s46, s46, 7
	s_ashr_i32 s55, s54, 31
	v_or_b32_e32 v166, s75, v184
	global_load_dword v15, v1, s[50:51]
	s_ashr_i32 s47, s46, 31
	s_lshl_b64 s[50:51], s[54:55], 1
	s_waitcnt vmcnt(3)
	v_mov_b32_e32 v14, v202
	v_ashrrev_i32_e32 v167, 31, v166
	s_add_u32 s50, s63, s50
	v_lshlrev_b64 v[2:3], 12, v[166:167]
	v_ashrrev_i32_e32 v0, 31, v14
	s_addc_u32 s51, s64, s51
	s_lshl_b64 s[58:59], s[54:55], 15
	v_lshrrev_b32_e32 v0, 28, v0
	v_lshl_add_u64 v[2:3], s[18:19], 0, v[2:3]
	s_add_u32 s33, s65, s58
	v_add_u32_e32 v0, v14, v0
	s_waitcnt vmcnt(2)
	v_lshl_add_u64 v[16:17], s[46:47], 1, v[2:3]
	s_addc_u32 s76, s66, s59
	v_ashrrev_i32_e32 v2, 4, v0
	v_and_b32_e32 v0, -16, v0
	s_waitcnt vmcnt(1)
	v_add_u32_e32 v22, 0x200, v14
	s_ashr_i32 s49, s48, 31
	v_sub_u32_e32 v24, v14, v0
	v_ashrrev_i32_e32 v0, 31, v22
	s_lshl_b64 s[52:53], s[48:49], 6
	v_ashrrev_i32_e32 v3, 31, v2
	v_lshrrev_b32_e32 v0, 28, v0
	v_lshl_add_u64 v[6:7], s[52:53], 0, v[2:3]
	v_add_u32_e32 v0, v22, v0
	v_lshlrev_b64 v[6:7], 10, v[6:7]
	v_ashrrev_i32_e32 v4, 4, v0
	v_lshl_add_u64 v[8:9], s[50:51], 0, v[6:7]
	v_lshlrev_b32_e32 v6, 3, v24
	v_ashrrev_i32_e32 v7, 31, v6
	v_ashrrev_i32_e32 v5, 31, v4
	v_lshl_add_u64 v[10:11], v[6:7], 1, v[8:9]
	v_lshl_add_u64 v[8:9], s[52:53], 0, v[4:5]
	v_and_b32_e32 v0, -16, v0
	v_lshlrev_b64 v[8:9], 10, v[8:9]
	v_sub_u32_e32 v25, v22, v0
	s_sub_i32 s74, s36, s48
	v_lshl_add_u64 v[12:13], s[50:51], 0, v[8:9]
	s_lshl_b64 s[50:51], s[48:49], 7
	v_lshlrev_b32_e32 v8, 3, v25
	s_add_u32 s50, s33, s50
	v_lshlrev_b32_e32 v0, 4, v14
	v_ashrrev_i32_e32 v20, 3, v14
	v_ashrrev_i32_e32 v9, 31, v8
	s_addc_u32 s51, s76, s51
	v_and_b32_e32 v0, 0x70, v0
	v_ashrrev_i32_e32 v21, 31, v20
	v_lshl_add_u64 v[12:13], v[8:9], 1, v[12:13]
	global_load_dwordx4 v[112:115], v[10:11], off
	global_load_dwordx4 v[116:119], v[12:13], off
	v_lshl_add_u64 v[18:19], s[50:51], 0, v[0:1]
	v_lshlrev_b64 v[10:11], 15, v[20:21]
	v_ashrrev_i32_e32 v22, 3, v22
	v_bfe_u32 v165, v14, 5, 1
	v_lshl_add_u64 v[12:13], v[18:19], 0, v[10:11]
	v_ashrrev_i32_e32 v23, 31, v22
	v_lshlrev_b32_e32 v168, 4, v165
	global_load_dwordx4 v[120:123], v[12:13], off
	v_lshlrev_b64 v[12:13], 15, v[22:23]
	v_mov_b32_e32 v169, v1
	v_lshl_add_u64 v[18:19], v[18:19], 0, v[12:13]
	v_lshl_add_u64 v[16:17], v[16:17], 0, v[168:169]
	global_load_dwordx4 v[156:159], v[18:19], off
	global_load_dwordx4 v[124:127], v[16:17], off
	global_load_dwordx4 v[128:131], v[16:17], off offset:32
	global_load_dwordx4 v[132:135], v[16:17], off offset:64
	global_load_dwordx4 v[136:139], v[16:17], off offset:96
	global_load_dwordx4 v[140:143], v[16:17], off offset:128
	global_load_dwordx4 v[144:147], v[16:17], off offset:160
	global_load_dwordx4 v[148:151], v[16:17], off offset:192
	global_load_dwordx4 v[152:155], v[16:17], off offset:224
	v_readfirstlane_b32 s33, v14
	v_mul_lo_u32 v188, v2, s70
	v_lshlrev_b32_e32 v189, 4, v24
	v_add3_u32 v16, 0, v188, v189
	v_mul_lo_u32 v190, v4, s70
	v_lshlrev_b32_e32 v191, 4, v25
	v_add_u32_e32 v192, 0, v0
	v_mul_lo_u32 v193, v20, s71
	s_cmpk_gt_i32 s33, 0xff
	v_add_u32_e32 v0, v192, v193
	v_mul_lo_u32 v194, v22, s71
	s_cselect_b64 s[50:51], -1, 0
	s_cmpk_lt_i32 s33, 0x100
	v_and_b32_e32 v169, 31, v14
	s_cselect_b64 s[52:53], -1, 0
	s_cmp_lt_i32 s74, 1
	s_mov_b32 s49, 0
	s_waitcnt vmcnt(11)
	ds_write_b128 v16, v[112:115]
	v_add3_u32 v16, 0, v190, v191
	s_waitcnt vmcnt(10)
	ds_write_b128 v16, v[116:119]
	s_waitcnt vmcnt(9)
	ds_write_b128 v0, v[120:123] offset:34816
	v_add_u32_e32 v0, v192, v194
	s_waitcnt vmcnt(8)
	ds_write_b128 v0, v[156:159] offset:34816
	s_waitcnt lgkmcnt(0)
	s_barrier
; #define ATT_LOAD(tile) do { const size_t key0 = (size_t)(tile) * 64; \
;         _Pragma("unroll") for (int i = 0; i < G::KC; ++i) kreg[i] = *(const u32x4*)(kbase + (key0 + krow_[i]) * kstride + kcc_[i] * 8); \
;         _Pragma("unroll") for (int i = 0; i < 2; ++i) { const int cid = tid + i * 512; vreg[i] = *(const u32x4*)(vtbase + (size_t)(cid >> 3) * M + key0 + (cid & 7) * 8); } } while (0)
; template <int DQK, int MODE> ...
;     ...
;     f32x16 O[4];
; #pragma unroll
;     for (int i = 0; i < 4; ++i)
; #pragma unroll
;         for (int j = 0; j < 16; ++j) O[i][j] = 0.f;
;     float m = m_init, l = l_init;
;     const int nt = tile_hi - tile_lo;
;     u32x4 kreg[G::KC], vreg[2];
;     int krow_[G::KC], kcc_[G::KC];
; #pragma unroll
;     for (int i = 0; i < G::KC; ++i) { const int cid = tid + i * 512; krow_[i] = cid / (DQK / 8); kcc_[i] = cid % (DQK / 8); }
;     ...
;     const bool late = __builtin_amdgcn_readfirstlane(tid >> 6) >= 4;
;     bf16x8 pf[4]; bool have_pf = false; int vprev = 0;
; #pragma unroll
;     for (int i = 0; i < 4; ++i) pf[i] = (bf16x8){0, 0, 0, 0, 0, 0, 0, 0};
;     ATT_LOAD(tile_lo); ATT_WRITE(0, 0);
;     __syncthreads();
;     int vcur = 0;
	s_cbranch_scc1 .LBB0_1137
	s_lshl_b32 s33, s48, 6
	v_lshl_add_u32 v0, v165, 4, 0
	s_addk_i32 s33, 0xbb
	v_mad_u32_u24 v195, v169, s71, v0
	v_mad_u32_u24 v196, v169, s70, v0
	v_lshl_or_b32 v0, v165, 2, s33
	s_ashr_i32 s33, s57, 31
	s_add_u32 s76, s57, -2
	s_addc_u32 s77, s33, -1
	s_ashr_i32 s57, s56, 31
	v_mov_b64_e32 v[16:17], s[56:57]
	v_cmp_gt_i64_e32 vcc, s[76:77], v[16:17]
	s_and_b64 s[78:79], vcc, exec
	s_cselect_b32 s57, s77, s57
	s_cselect_b32 s56, s76, s56
	s_lshl_b64 s[76:77], s[56:57], 7
	v_mul_f32_e32 v198, 0x3fb8aa3b, v15
	v_add_u32_e32 v15, s75, v184
	s_add_u32 s58, s76, s58
	v_sub_u32_e32 v197, v0, v15
	s_addc_u32 s59, s77, s59
	v_and_b32_e32 v0, 7, v14
	s_lshl_b64 s[56:57], s[56:57], 16
	v_lshl_add_u64 v[10:11], v[10:11], 0, s[58:59]
	v_lshlrev_b32_e32 v0, 4, v0
	s_add_u32 s56, s56, 0x18c10000
	v_lshl_add_u64 v[10:11], v[10:11], 0, v[0:1]
	s_addc_u32 s57, s57, 0
	v_lshlrev_b64 v[4:5], 10, v[4:5]
	v_lshl_add_u64 v[170:171], v[10:11], 0, s[40:41]
	v_lshl_add_u64 v[10:11], v[12:13], 0, s[58:59]
	v_lshl_add_u64 v[4:5], s[56:57], 0, v[4:5]
	v_lshl_add_u64 v[8:9], s[54:55], 0, v[8:9]
	v_lshlrev_b64 v[2:3], 10, v[2:3]
	v_lshl_add_u64 v[10:11], v[10:11], 0, v[0:1]
	v_lshl_add_u64 v[174:175], v[8:9], 1, v[4:5]
	v_lshl_add_u64 v[2:3], s[56:57], 0, v[2:3]
	v_lshl_add_u64 v[4:5], s[54:55], 0, v[6:7]
	v_mov_b32_e32 v14, v1
	v_mov_b32_e32 v15, v1
	v_lshl_add_u64 v[172:173], v[10:11], 0, s[40:41]
	v_lshl_add_u64 v[176:177], v[4:5], 1, v[2:3]
	v_mov_b32_e32 v0, v1
	v_mov_b32_e32 v2, v1
	v_mov_b32_e32 v3, v1
	v_mov_b32_e32 v4, v1
	v_mov_b32_e32 v5, v1
	v_mov_b32_e32 v6, v1
	v_mov_b32_e32 v7, v1
	v_mov_b32_e32 v8, v1
	v_mov_b32_e32 v9, v1
	v_mov_b32_e32 v10, v1
	v_mov_b32_e32 v11, v1
	v_mov_b32_e32 v12, v1
	v_mov_b32_e32 v13, v1
	v_mov_b64_e32 v[78:79], v[14:15]
	v_mov_b64_e32 v[62:63], v[14:15]
	v_mov_b64_e32 v[46:47], v[14:15]
	v_mov_b64_e32 v[30:31], v[14:15]
	s_mov_b64 s[54:55], 0
	v_mov_b32_e32 v92, 0
	v_mov_b32_e32 v93, 0
	v_mov_b32_e32 v94, 0
	v_mov_b32_e32 v95, 0
	v_mov_b32_e32 v88, 0
	v_mov_b32_e32 v89, 0
	v_mov_b32_e32 v90, 0
	v_mov_b32_e32 v91, 0
	v_mov_b32_e32 v84, 0
	v_mov_b32_e32 v85, 0
	v_mov_b32_e32 v86, 0
	v_mov_b32_e32 v87, 0
	v_mov_b32_e32 v80, 0
	v_mov_b32_e32 v81, 0
	v_mov_b32_e32 v82, 0
	v_mov_b32_e32 v83, 0
	v_mov_b64_e32 v[76:77], v[12:13]
	v_mov_b64_e32 v[74:75], v[10:11]
	v_mov_b64_e32 v[72:73], v[8:9]
	v_mov_b64_e32 v[70:71], v[6:7]
	v_mov_b64_e32 v[68:69], v[4:5]
	v_mov_b64_e32 v[66:67], v[2:3]
	v_mov_b64_e32 v[64:65], v[0:1]
	v_mov_b64_e32 v[60:61], v[12:13]
	v_mov_b64_e32 v[58:59], v[10:11]
	v_mov_b64_e32 v[56:57], v[8:9]
	v_mov_b64_e32 v[54:55], v[6:7]
	v_mov_b64_e32 v[52:53], v[4:5]
	v_mov_b64_e32 v[50:51], v[2:3]
	v_mov_b64_e32 v[48:49], v[0:1]
	v_mov_b64_e32 v[44:45], v[12:13]
	v_mov_b64_e32 v[42:43], v[10:11]
	v_mov_b64_e32 v[40:41], v[8:9]
	v_mov_b64_e32 v[38:39], v[6:7]
	v_mov_b64_e32 v[36:37], v[4:5]
	v_mov_b64_e32 v[34:35], v[2:3]
	v_mov_b64_e32 v[32:33], v[0:1]
	v_mov_b64_e32 v[28:29], v[12:13]
	v_mov_b64_e32 v[26:27], v[10:11]
	v_mov_b64_e32 v[24:25], v[8:9]
	v_mov_b64_e32 v[22:23], v[6:7]
	v_mov_b64_e32 v[20:21], v[4:5]
	v_mov_b64_e32 v[18:19], v[2:3]
	v_mov_b64_e32 v[16:17], v[0:1]
	v_mov_b32_e32 v187, v185
	s_mov_b32 s75, 0
	s_mov_b32 s77, 0
	s_waitcnt vmcnt(0)

; #define LAS __attribute__((address_space(3)))
; template <int DQK, int MODE> ...
;     ...
;             for (int dc = 0; dc < DQK / 16; ++dc) {
;                 const bf16x8 ka = *(const LAS bf16x8*)(kb + r32 * G::KROW + dc * 32 + hh * 16);
;                 const bf16x8 kb2 = *(const LAS bf16x8*)(kb + (32 + r32) * G::KROW + dc * 32 + hh * 16);
;                 S0 = __builtin_amdgcn_mfma_f32_32x32x16_bf16(ka, qf[dc], S0, 0, 0, 0);
;                 S1 = __builtin_amdgcn_mfma_f32_32x32x16_bf16(kb2, qf[dc], S1, 0, 0, 0);
;             }
;             if (MODE == 1) {
;                 const LAS float* rpbL = (const LAS float*)(lds + G::RPB_OFF);
;                 const int c = a0; int cs = c - 8; cs = cs < 0 ? 0 : (cs > 48 ? 48 : cs);
;                 const LAS float* rrow = rpbL + (tile + a1) * 31;
;                 int cb = 4 * hh + 15 - c, vb_ = 4 * hh - cs; asm volatile("" : "+v"(cb), "+v"(vb_));
;                 float bb0[16], bb1[16];
; #pragma unroll
;                 for (int j = 0; j < 16; ++j) {
;                     const int kk = (j & 3) + 8 * (j >> 2);
;                     int i0 = kk + cb; i0 = i0 < 0 ? 0 : (i0 > 30 ? 30 : i0); int i1 = kk + 32 + cb; i1 = i1 < 0 ? 0 : (i1 > 30 ? 30 : i1);
;                     bb0[j] = rrow[i0]; bb1[j] = rrow[i1];
;                 }
; #pragma unroll
;                 for (int j = 0; j < 16; ++j) asm volatile("" : "+v"(bb0[j]), "+v"(bb1[j]));
; #pragma unroll
;                 for (int j = 0; j < 16; ++j) {
;                     const int kk = (j & 3) + 8 * (j >> 2);
;                     S0[j] = ((unsigned)(kk + vb_) < 16u) ? S0[j] + bb0[j] : -INFINITY;
;                     S1[j] = ((unsigned)(kk + 32 + vb_) < 16u) ? S1[j] + bb1[j] : -INFINITY;
;                 }
;             }
;             if (MODE == 2) {
;                 const int dbase = tile * 64 - a0;
; #pragma unroll
;                 for (int j = 0; j < 16; ++j) {
;                     const int d0 = dbase + crow(j, hh), d1 = d0 + 32;
;                     S0[j] = (d0 >= -128 && d0 <= 128) ? S0[j] : -INFINITY;
;                     S1[j] = (d1 >= -128 && d1 <= 128) ? S1[j] : -INFINITY;
;                 }
;             }
;             float pmax = S0[0];
; #pragma unroll
;             for (int j = 1; j < 16; ++j) pmax = fmaxf(pmax, S0[j]);
; #pragma unroll
;             for (int j = 0; j < 16; ++j) pmax = fmaxf(pmax, S1[j]);
.LBB0_1121:
	s_mul_i32 s33, s77, 0x4400
	v_add_u32_e32 v0, s33, v196
	ds_read_b128 v[2:5], v0
	ds_read_b128 v[6:9], v0 offset:32
	s_waitcnt lgkmcnt(1)
	v_mfma_f32_32x32x16_bf16 v[80:95], v[2:5], v[124:127], 0
	ds_read_b128 v[2:5], v0 offset:8704
	ds_read_b128 v[10:13], v0 offset:8736
	s_waitcnt lgkmcnt(1)
	v_mfma_f32_32x32x16_bf16 v[96:111], v[2:5], v[124:127], 0
	s_nop 0
	v_mfma_f32_32x32x16_bf16 v[80:95], v[6:9], v[128:131], v[80:95]
	ds_read_b128 v[2:5], v0 offset:64
	ds_read_b128 v[6:9], v0 offset:96
	s_waitcnt lgkmcnt(2)
	v_mfma_f32_32x32x16_bf16 v[96:111], v[10:13], v[128:131], v[96:111]
	s_waitcnt lgkmcnt(1)
	v_mfma_f32_32x32x16_bf16 v[80:95], v[2:5], v[132:135], v[80:95]
	ds_read_b128 v[2:5], v0 offset:8768
	ds_read_b128 v[10:13], v0 offset:8800
	s_waitcnt lgkmcnt(1)
	v_mfma_f32_32x32x16_bf16 v[96:111], v[2:5], v[132:135], v[96:111]
	s_nop 0
	v_mfma_f32_32x32x16_bf16 v[80:95], v[6:9], v[136:139], v[80:95]
	ds_read_b128 v[2:5], v0 offset:128
	ds_read_b128 v[6:9], v0 offset:160
	s_waitcnt lgkmcnt(2)
	v_mfma_f32_32x32x16_bf16 v[96:111], v[10:13], v[136:139], v[96:111]
	s_waitcnt lgkmcnt(1)
	v_mfma_f32_32x32x16_bf16 v[80:95], v[2:5], v[140:143], v[80:95]
	ds_read_b128 v[2:5], v0 offset:8832
	ds_read_b128 v[10:13], v0 offset:8864
	s_waitcnt lgkmcnt(1)
	v_mfma_f32_32x32x16_bf16 v[96:111], v[2:5], v[140:143], v[96:111]
	s_nop 0
	v_mfma_f32_32x32x16_bf16 v[80:95], v[6:9], v[144:147], v[80:95]
	ds_read_b128 v[2:5], v0 offset:192
	ds_read_b128 v[6:9], v0 offset:224
	s_waitcnt lgkmcnt(2)
	v_mfma_f32_32x32x16_bf16 v[96:111], v[10:13], v[144:147], v[96:111]
	s_waitcnt lgkmcnt(1)
	v_mfma_f32_32x32x16_bf16 v[80:95], v[2:5], v[148:151], v[80:95]
	ds_read_b128 v[2:5], v0 offset:8896
	ds_read_b128 v[10:13], v0 offset:8928
	v_subrev_u32_e32 v0, 59, v197
	v_cmp_gt_u32_e32 vcc, s72, v0
	s_waitcnt lgkmcnt(1)
	v_mfma_f32_32x32x16_bf16 v[96:111], v[2:5], v[148:151], v[96:111]
	v_subrev_u32_e32 v2, 27, v197
	v_subrev_u32_e32 v3, 58, v197
	v_subrev_u32_e32 v4, 26, v197
	v_subrev_u32_e32 v5, 57, v197
	s_nop 0
	v_mfma_f32_32x32x16_bf16 v[80:95], v[6:9], v[152:155], v[80:95]
	v_subrev_u32_e32 v6, 25, v197
	v_subrev_u32_e32 v7, 56, v197
	v_subrev_u32_e32 v8, 24, v197
	v_subrev_u32_e32 v9, 51, v197
	s_waitcnt lgkmcnt(0)
	v_mfma_f32_32x32x16_bf16 v[96:111], v[10:13], v[152:155], v[96:111]
	s_nop 5
	v_cndmask_b32_e32 v0, v186, v80, vcc
	v_cmp_gt_u32_e32 vcc, s72, v2
	v_subrev_u32_e32 v10, 19, v197
	v_max_f32_e32 v14, v0, v0
	s_nop 1
	v_cndmask_b32_e32 v2, v186, v96, vcc
	v_cmp_gt_u32_e32 vcc, s72, v3
	s_nop 1
	v_cndmask_b32_e32 v3, v186, v81, vcc
	v_cmp_gt_u32_e32 vcc, s72, v4
	s_nop 1
	v_cndmask_b32_e32 v4, v186, v97, vcc
	v_cmp_gt_u32_e32 vcc, s72, v5
	s_nop 1
	v_cndmask_b32_e32 v5, v186, v82, vcc
	v_cmp_gt_u32_e32 vcc, s72, v6
	s_nop 1
	v_cndmask_b32_e32 v6, v186, v98, vcc
	v_cmp_gt_u32_e32 vcc, s72, v7
	s_nop 1
	v_cndmask_b32_e32 v7, v186, v83, vcc
	v_cmp_gt_u32_e32 vcc, s72, v8
	s_nop 1
	v_cndmask_b32_e32 v8, v186, v99, vcc
	v_cmp_gt_u32_e32 vcc, s72, v9
	s_nop 1
	v_cndmask_b32_e32 v9, v186, v84, vcc
	v_cmp_gt_u32_e32 vcc, s72, v10
	v_subrev_u32_e32 v10, 50, v197
	s_nop 0
	v_cndmask_b32_e32 v11, v186, v100, vcc
	v_cmp_gt_u32_e32 vcc, s72, v10
	v_subrev_u32_e32 v10, 18, v197
	s_nop 0
	v_cndmask_b32_e32 v12, v186, v85, vcc
	v_cmp_gt_u32_e32 vcc, s72, v10
	v_subrev_u32_e32 v10, 49, v197
	s_nop 0
	v_cndmask_b32_e32 v13, v186, v101, vcc
	v_cmp_gt_u32_e32 vcc, s72, v10
	v_subrev_u32_e32 v10, 17, v197
	s_nop 0
	v_cndmask_b32_e32 v15, v186, v86, vcc
	v_cmp_gt_u32_e32 vcc, s72, v10
	v_subrev_u32_e32 v10, 48, v197
	s_nop 0
	v_cndmask_b32_e32 v80, v186, v102, vcc
	v_cmp_gt_u32_e32 vcc, s72, v10
	v_add_u32_e32 v10, -16, v197
	s_nop 0
	v_cndmask_b32_e32 v81, v186, v87, vcc
	v_cmp_gt_u32_e32 vcc, s72, v10
	v_subrev_u32_e32 v10, 43, v197
	s_nop 0
	v_cndmask_b32_e32 v82, v186, v103, vcc
	v_cmp_gt_u32_e32 vcc, s72, v10
	v_add_u32_e32 v10, -11, v197
	s_nop 0
	v_cndmask_b32_e32 v83, v186, v88, vcc
	v_cmp_gt_u32_e32 vcc, s72, v10
	v_subrev_u32_e32 v10, 42, v197
	s_nop 0
	v_cndmask_b32_e32 v84, v186, v104, vcc
	v_cmp_gt_u32_e32 vcc, s72, v10
	v_add_u32_e32 v10, -10, v197
	s_nop 0
	v_cndmask_b32_e32 v85, v186, v89, vcc
	v_cmp_gt_u32_e32 vcc, s72, v10
	v_subrev_u32_e32 v10, 41, v197
	s_nop 0
	v_cndmask_b32_e32 v86, v186, v105, vcc
	v_cmp_gt_u32_e32 vcc, s72, v10
	v_add_u32_e32 v10, -9, v197
	s_nop 0
	v_cndmask_b32_e32 v87, v186, v90, vcc
	v_cmp_gt_u32_e32 vcc, s72, v10
	v_subrev_u32_e32 v10, 40, v197
	s_nop 0
	v_cndmask_b32_e32 v88, v186, v106, vcc
	v_cmp_gt_u32_e32 vcc, s72, v10
	v_add_u32_e32 v10, -8, v197
	s_nop 0
	v_cndmask_b32_e32 v89, v186, v91, vcc
	v_cmp_gt_u32_e32 vcc, s72, v10
	v_subrev_u32_e32 v10, 35, v197
	s_nop 0
	v_cndmask_b32_e32 v90, v186, v107, vcc
	v_cmp_gt_u32_e32 vcc, s72, v10
	v_add_u32_e32 v10, -3, v197
	s_nop 0
	v_cndmask_b32_e32 v91, v186, v92, vcc
	v_cmp_gt_u32_e32 vcc, s72, v10
	v_subrev_u32_e32 v10, 34, v197
	s_nop 0
	v_cndmask_b32_e32 v92, v186, v108, vcc
	v_cmp_gt_u32_e32 vcc, s72, v10
	v_add_u32_e32 v10, -2, v197
	s_nop 0
	v_cndmask_b32_e32 v93, v186, v93, vcc
	v_cmp_gt_u32_e32 vcc, s72, v10
	v_subrev_u32_e32 v10, 33, v197
	s_nop 0
	v_cndmask_b32_e32 v97, v186, v109, vcc
	v_cmp_gt_u32_e32 vcc, s72, v10
	v_add_u32_e32 v10, -1, v197
	s_nop 0
	v_cndmask_b32_e32 v94, v186, v94, vcc
	v_cmp_gt_u32_e32 vcc, s72, v10
	v_subrev_u32_e32 v10, 32, v197
	s_nop 0
	v_cndmask_b32_e32 v99, v186, v110, vcc
	v_cmp_gt_u32_e32 vcc, s72, v10
	v_max_f32_e32 v10, v3, v3
	v_max_f32_e32 v10, v14, v10
	v_max3_f32 v10, v10, v5, v7
	v_max3_f32 v10, v10, v9, v12
	v_max3_f32 v10, v10, v15, v81
	v_max3_f32 v10, v10, v83, v85
	v_max3_f32 v10, v10, v87, v89
	v_cndmask_b32_e32 v95, v186, v95, vcc
	v_max3_f32 v10, v10, v91, v93
	v_max3_f32 v10, v10, v94, v95
	v_max3_f32 v10, v10, v2, v4
	v_max3_f32 v10, v10, v6, v8
	v_max3_f32 v10, v10, v11, v13
	v_max3_f32 v10, v10, v80, v82
	v_max3_f32 v10, v10, v84, v86
	v_cmp_gt_u32_e32 vcc, s72, v197
	v_max3_f32 v10, v10, v88, v90
	v_max3_f32 v10, v10, v92, v97
	v_cndmask_b32_e32 v101, v186, v111, vcc
	v_max3_f32 v10, v10, v99, v101
	v_mov_b32_e32 v14, v10
	s_nop 1
	v_permlane32_swap_b32_e32 v10, v14
	v_max_f32_e32 v14, v14, v14
	v_max_f32_e32 v10, v10, v10
	v_max_f32_e32 v10, v10, v14
	v_sub_f32_e32 v14, v10, v198
	v_cmp_ge_f32_e32 vcc, s73, v14
	s_cmp_eq_u64 vcc, exec
	s_cbranch_scc1 .LBB0_1123
; template <int DQK, int MODE> ...
;     ...
;             if (!__all(pmax - m <= 8.0f)) {
;                 const float mn2 = fmaxf(m, pmax); const float alpha = __builtin_amdgcn_exp2f(m - mn2); m = mn2; l *= alpha;
; #pragma unroll
;                 for (int i = 0; i < 4; ++i)
; #pragma unroll
;                     for (int j = 0; j < 16; ++j) O[i][j] *= alpha;
;             }
	v_max_f32_e32 v10, v10, v10
	v_max_f32_e32 v14, v198, v198
	v_max_f32_e32 v14, v14, v10
	v_sub_f32_e32 v10, v198, v14
	v_exp_f32_e32 v10, v10
	v_mov_b32_e32 v198, v14
	v_pk_mul_f32 v[78:79], v[78:79], v[10:11] op_sel_hi:[1,0]
	v_pk_mul_f32 v[76:77], v[76:77], v[10:11] op_sel_hi:[1,0]
	v_pk_mul_f32 v[74:75], v[74:75], v[10:11] op_sel_hi:[1,0]
	v_pk_mul_f32 v[72:73], v[72:73], v[10:11] op_sel_hi:[1,0]
	v_pk_mul_f32 v[70:71], v[70:71], v[10:11] op_sel_hi:[1,0]
	v_pk_mul_f32 v[68:69], v[68:69], v[10:11] op_sel_hi:[1,0]
	v_pk_mul_f32 v[66:67], v[66:67], v[10:11] op_sel_hi:[1,0]
	v_pk_mul_f32 v[64:65], v[64:65], v[10:11] op_sel_hi:[1,0]
	v_pk_mul_f32 v[62:63], v[62:63], v[10:11] op_sel_hi:[1,0]
	v_pk_mul_f32 v[60:61], v[60:61], v[10:11] op_sel_hi:[1,0]
	v_pk_mul_f32 v[58:59], v[58:59], v[10:11] op_sel_hi:[1,0]
	v_pk_mul_f32 v[56:57], v[56:57], v[10:11] op_sel_hi:[1,0]
	v_pk_mul_f32 v[54:55], v[54:55], v[10:11] op_sel_hi:[1,0]
	v_pk_mul_f32 v[52:53], v[52:53], v[10:11] op_sel_hi:[1,0]
	v_pk_mul_f32 v[50:51], v[50:51], v[10:11] op_sel_hi:[1,0]
	v_pk_mul_f32 v[48:49], v[48:49], v[10:11] op_sel_hi:[1,0]
	v_pk_mul_f32 v[46:47], v[46:47], v[10:11] op_sel_hi:[1,0]
	v_pk_mul_f32 v[44:45], v[44:45], v[10:11] op_sel_hi:[1,0]
	v_pk_mul_f32 v[42:43], v[42:43], v[10:11] op_sel_hi:[1,0]
	v_pk_mul_f32 v[40:41], v[40:41], v[10:11] op_sel_hi:[1,0]
	v_pk_mul_f32 v[38:39], v[38:39], v[10:11] op_sel_hi:[1,0]
	v_pk_mul_f32 v[36:37], v[36:37], v[10:11] op_sel_hi:[1,0]
	v_pk_mul_f32 v[34:35], v[34:35], v[10:11] op_sel_hi:[1,0]
	v_pk_mul_f32 v[32:33], v[32:33], v[10:11] op_sel_hi:[1,0]
	v_pk_mul_f32 v[30:31], v[30:31], v[10:11] op_sel_hi:[1,0]
	v_pk_mul_f32 v[28:29], v[28:29], v[10:11] op_sel_hi:[1,0]
	v_pk_mul_f32 v[26:27], v[26:27], v[10:11] op_sel_hi:[1,0]
	v_pk_mul_f32 v[24:25], v[24:25], v[10:11] op_sel_hi:[1,0]
	v_pk_mul_f32 v[22:23], v[22:23], v[10:11] op_sel_hi:[1,0]
	v_pk_mul_f32 v[20:21], v[20:21], v[10:11] op_sel_hi:[1,0]
	v_pk_mul_f32 v[18:19], v[18:19], v[10:11] op_sel_hi:[1,0]
	v_pk_mul_f32 v[16:17], v[16:17], v[10:11] op_sel_hi:[1,0]
	v_mul_f32_e32 v187, v187, v10
